# merge epilogue hand-rewritten in both instances: 8-block load ring, counted vmcnt, streamed write-through stores
# speedup vs baseline: 1.0047x; 1.0047x over previous
.LBB0_537:
	s_or_b64 exec, exec, s[0:1]
	s_and_b64 s[0:1], s[36:37], exec
	s_cselect_b32 s28, 16, 0x1000
	s_add_u32 s64, s76, 0x13d00000
	s_addc_u32 s65, s77, 0
	s_bfe_u32 s68, s96, 0x20006
	s_mul_i32 s0, s68, 0x3700
	s_add_i32 s71, s0, 0
	s_and_b32 s0, s96, 0xffffff00
	s_lshr_b32 s74, s96, 8
	s_add_i32 s84, s0, 0
	s_lshl_b32 s11, s74, 5
	s_add_i32 s80, s84, 0x12600
	s_cmpk_lt_u32 s96, 0x540
	v_readlane_b32 s20, v255, 31
	s_cselect_b64 s[40:41], -1, 0
	s_add_i32 s12, s20, -4
	s_lshl_b32 s13, s12, 2
	s_lshl_b32 s22, s12, 10
	s_cmpk_lt_u32 s96, 0x440
	s_cselect_b64 s[42:43], -1, 0
	s_lshl_b32 s66, s20, 10
	s_cmpk_lt_u32 s96, 0x340
	s_cselect_b64 s[46:47], -1, 0
	s_add_i32 s14, s20, 4
	s_lshl_b32 s15, s14, 2
	s_lshl_b32 s23, s14, 10
	s_cmpk_lt_u32 s96, 0x240
	s_cselect_b64 s[48:49], -1, 0
	s_add_i32 s16, s20, 8
	s_lshl_b32 s17, s16, 2
	s_lshl_b32 s24, s16, 10
	s_cmp_eq_u32 s20, 4
	s_cselect_b64 s[50:51], -1, 0
	s_cmp_eq_u32 s20, 2
	s_mov_b32 s0, 0xfc00000
	s_cselect_b32 s38, s0, 0x13d00000
	s_add_u32 s8, s76, s6
	s_addc_u32 s9, s77, 0
	s_mul_i32 s0, s20, 0x2400
	s_add_i32 s1, 0, 0x1a900
	s_add_i32 s81, s1, s0
	s_lshl_b32 s0, s74, 7
	s_add_i32 s83, s0, 0
	s_add_i32 s82, s81, 0x2000
	s_add_i32 s83, s83, 0x14800
	s_add_i32 s84, s84, 0x12400
	s_lshl_b32 s29, s20, 5
	s_add_u32 s6, s64, s6
	s_addc_u32 s7, s65, 0
	s_lshl_b32 s85, s33, 10
	s_add_u32 s18, s76, 0x10000
	v_writelane_b32 v255, s96, 33
	s_addc_u32 s19, s77, 0
	v_lshl_or_b32 v11, s68, 4, v9
	v_writelane_b32 v255, s18, 34
	v_add_u32_e32 v25, 1, v11
	v_lshlrev_b32_e32 v27, 3, v38
	v_writelane_b32 v255, s19, 35
	v_lshlrev_b32_e32 v10, 7, v25
	v_and_b32_e32 v22, 8, v27
	s_add_i32 s0, 0, 0x1cd00
	s_add_i32 s18, 0, 0x1f100
	v_add3_u32 v91, s1, v10, v22
	v_add3_u32 v92, s0, v10, v22
	v_add3_u32 v93, s18, v10, v22
	v_lshlrev_b32_e32 v10, 8, v25
	s_add_i32 s19, 0, 0x23900
	v_add3_u32 v28, s19, v10, v22
	v_lshlrev_b32_e32 v10, 7, v11
	v_add3_u32 v94, s1, v10, v22
	v_add3_u32 v95, s0, v10, v22
	v_add3_u32 v96, s18, v10, v22
	v_lshlrev_b32_e32 v10, 8, v11
	v_add3_u32 v29, s19, v10, v22
	v_add_u32_e32 v10, 1, v89
	s_add_i32 s19, 0, 0x21500
	v_lshl_add_u32 v32, v10, 7, s19
	v_xor_b32_e32 v10, v10, v39
	v_lshlrev_b32_e32 v10, 4, v10
	v_and_b32_e32 v33, 0x70, v10
	v_lshlrev_b32_e32 v10, 7, v89
	v_add_u32_e32 v34, s19, v10
	s_add_i32 s19, 0, 0x12800
	s_cmp_lg_u32 s12, 16
	v_add_u32_e32 v36, s19, v10
	v_or_b32_e32 v10, s13, v38
	s_cselect_b64 vcc, -1, 0
	v_xor_b32_e32 v22, v89, v39
	v_cndmask_b32_e32 v98, 64, v10, vcc
	v_bitop3_b32 v10, v38, v39, s13 bitop3:0x36
	v_lshlrev_b32_e32 v22, 4, v22
	v_and_or_b32 v10, v10, 7, v41
	v_and_b32_e32 v35, 0x70, v22
	v_lshlrev_b32_e32 v22, 4, v10
	v_mov_b32_e32 v10, 0
	v_mov_b32_e32 v23, v10
	s_cmp_lg_u32 s20, 16
	v_lshl_add_u64 v[48:49], s[4:5], 0, v[22:23]
	v_or_b32_e32 v22, s3, v38
	s_cselect_b64 vcc, -1, 0
	v_cndmask_b32_e32 v99, 64, v22, vcc
	v_bitop3_b32 v22, v38, v39, s3 bitop3:0x36
	v_and_or_b32 v22, v22, 7, v41
	v_lshlrev_b32_e32 v22, 4, v22
	s_cmp_lg_u32 s14, 16
	v_lshl_add_u64 v[50:51], s[4:5], 0, v[22:23]
	v_or_b32_e32 v22, s15, v38
	s_cselect_b64 vcc, -1, 0
	v_cndmask_b32_e32 v100, 64, v22, vcc
	v_bitop3_b32 v22, v38, v39, s15 bitop3:0x36
	v_and_or_b32 v22, v22, 7, v41
	v_lshlrev_b32_e32 v22, 4, v22
	s_cmp_lg_u32 s16, 16
	v_lshl_add_u64 v[52:53], s[4:5], 0, v[22:23]
	v_or_b32_e32 v22, s17, v38
	s_cselect_b64 vcc, -1, 0
	v_cndmask_b32_e32 v101, 64, v22, vcc
	v_bitop3_b32 v22, v38, v39, s17 bitop3:0x36
	v_and_or_b32 v22, v22, 7, v41
	v_lshlrev_b32_e32 v22, 4, v22
	v_lshl_add_u64 v[54:55], s[4:5], 0, v[22:23]
	v_xor_b32_e32 v22, v38, v20
	s_movk_i32 s10, 0x3700
	v_or_b32_e32 v22, v22, v41
	v_lshlrev_b32_e32 v41, 5, v9
	v_lshrrev_b32_e32 v45, 7, v42
	v_cmp_gt_u32_e64 s[0:1], 16, v40
	v_or_b32_e32 v103, v27, v41
	v_lshl_add_u32 v104, v40, 2, s71
	v_add_u32_e32 v40, s71, v41
	v_lshrrev_b32_e32 v41, 2, v9
	v_mul_lo_u32 v45, v45, s10
	v_or_b32_e32 v41, v90, v41
	v_add_u32_e32 v67, 0, v45
	v_bfe_u32 v45, v42, 3, 4
	v_mul_u32_u24_e32 v41, 0x48, v41
	v_and_b32_e32 v21, 12, v21
	v_mul_u32_u24_e32 v45, 0x48, v45
	v_or_b32_e32 v24, s11, v90
	v_add_lshl_u32 v105, v21, v41, 1
	v_lshl_or_b32 v21, v89, 6, v8
	v_add_lshl_u32 v8, v45, v8, 1
	v_mov_b32_e32 v45, v10
	v_and_b32_e32 v26, 7, v25
	v_lshl_add_u64 v[60:61], s[6:7], 0, v[44:45]
	v_cmp_eq_u32_e64 s[6:7], 0, v42
	v_lshrrev_b32_e32 v42, 3, v24
	v_and_b32_e32 v62, 8, v42
	v_bitop3_b32 v63, v42, v26, 5 bitop3:0x6c
	v_or_b32_e32 v63, v63, v62
	v_lshlrev_b32_e32 v68, 4, v63
	v_add_u32_e32 v63, 64, v24
	v_bitop3_b32 v45, v42, v25, 7 bitop3:0x78
	v_lshrrev_b32_e32 v64, 3, v63
	v_xor_b32_e32 v69, v42, v20
	v_bitop3_b32 v42, v42, v20, 5 bitop3:0x6c
	v_and_b32_e32 v65, 8, v64
	v_or_b32_e32 v42, v42, v62
	v_bitop3_b32 v62, v64, v20, 5 bitop3:0x6c
	v_or_b32_e32 v62, v62, v65
	v_lshlrev_b32_e32 v108, 4, v69
	v_lshlrev_b32_e32 v69, 4, v62
	v_or_b32_e32 v62, 16, v24
	v_lshlrev_b32_e32 v22, 4, v22
	v_lshlrev_b32_e32 v71, 1, v63
	v_lshrrev_b32_e32 v63, 3, v62
	v_lshl_add_u64 v[56:57], s[4:5], 0, v[22:23]
	v_xor_b32_e32 v22, v88, v20
	v_bitop3_b32 v26, v64, v26, 5 bitop3:0x6c
	v_bitop3_b32 v64, v63, v25, 7 bitop3:0x78
	v_lshlrev_b32_e32 v22, 4, v22
	v_or_b32_e32 v26, v26, v65
	v_lshlrev_b32_e32 v111, 4, v64
	v_and_b32_e32 v64, 8, v63
	v_bitop3_b32 v65, v63, v25, 7 bitop3:0x28
	s_movk_i32 s18, 0x48
	v_lshl_add_u64 v[58:59], s[8:9], 0, v[22:23]
	v_or_b32_e32 v23, s11, v9
	v_or_b32_e32 v65, v65, v64
	v_mul_u32_u24_e32 v30, 0x48, v11
	v_mul_u32_u24_e32 v31, 0x48, v9
	v_lshlrev_b32_e32 v97, 2, v11
	v_or_b32_e32 v22, 16, v90
	v_lshlrev_b32_e32 v72, 4, v65
	v_add_u32_e32 v65, 0x50, v24
	v_mul_lo_u32 v23, v23, s18
	v_mad_u32_u24 v11, v11, s18, 32
	v_lshlrev_b32_e32 v70, 1, v24
	v_add_lshl_u32 v109, v24, v30, 1
	v_add_lshl_u32 v110, v24, v31, 1
	v_lshrrev_b32_e32 v73, 3, v65
	v_xor_b32_e32 v75, v63, v20
	v_bitop3_b32 v63, v63, v20, 7 bitop3:0x6c
	v_add_lshl_u32 v113, v62, v30, 1
	v_add_lshl_u32 v115, v30, v90, 1
	v_add_lshl_u32 v116, v22, v30, 1
	v_add_u32_e32 v30, 0x480, v23
	v_add_lshl_u32 v119, v11, v90, 1
	v_add_lshl_u32 v120, v11, v22, 1
	v_or_b32_e32 v11, 32, v90
	v_lshlrev_b32_e32 v123, 2, v24
	v_or_b32_e32 v24, 1, v90
	v_cmp_eq_u32_e32 vcc, v90, v9
	v_lshlrev_b32_e32 v106, 5, v20
	v_and_b32_e32 v74, 8, v73
	v_bitop3_b32 v25, v73, v25, 7 bitop3:0x28
	v_or_b32_e32 v63, v63, v64
	v_bitop3_b32 v20, v73, v20, 7 bitop3:0x6c
	v_lshlrev_b32_e32 v73, 1, v62
	v_add_lshl_u32 v114, v62, v31, 1
	v_add_lshl_u32 v118, v30, v90, 1
	v_add_lshl_u32 v122, v11, v30, 1
	v_lshlrev_b32_e32 v124, 2, v62
	v_or_b32_e32 v30, 2, v90
	v_cndmask_b32_e64 v62, 0, 1.0, vcc
	v_cmp_eq_u32_e32 vcc, v24, v9
	v_lshlrev_b32_e32 v112, 4, v75
	v_lshlrev_b32_e32 v75, 4, v63
	v_add_lshl_u32 v117, v90, v23, 1
	v_add_lshl_u32 v121, v11, v23, 1
	v_add_lshl_u32 v125, v90, v31, 1
	v_add_lshl_u32 v23, v11, v31, 1
	v_or_b32_e32 v31, 3, v90
	v_cndmask_b32_e64 v63, 0, 1.0, vcc
	v_cmp_eq_u32_e32 vcc, v30, v9
	v_cmp_eq_u32_e64 s[4:5], 0, v9
	v_mad_u32_u24 v37, v9, s18, 16
	v_cmp_lt_u32_e64 s[8:9], v90, v9
	v_cmp_gt_u32_e64 s[10:11], v90, v9
	v_cmp_lt_u32_e64 s[12:13], v24, v9
	v_cmp_lt_u32_e64 s[14:15], v30, v9
	v_cmp_gt_u32_e64 s[16:17], v30, v9
	v_cmp_lt_u32_e64 s[18:19], v31, v9
	v_cmp_gt_u32_e64 s[20:21], v31, v9
	v_cndmask_b32_e64 v64, 0, 1.0, vcc
	v_cmp_eq_u32_e32 vcc, v31, v9
	v_lshlrev_b32_e32 v9, 2, v9
	v_lshl_add_u32 v24, v38, 10, s97
	s_mov_b32 s3, 0xdc00
	v_add3_u32 v126, v24, v9, s3
	v_and_b32_e32 v9, 3, v39
	s_movk_i32 s25, 0x2400
	v_lshlrev_b32_e32 v43, 2, v21
	v_lshlrev_b32_e32 v21, 1, v21
	v_lshl_or_b32 v9, v9, 3, s29
	v_lshlrev_b32_e32 v24, 1, v41
	s_waitcnt lgkmcnt(0)
	s_barrier
	v_lshlrev_b32_e32 v66, 2, v89
	v_or_b32_e32 v25, v25, v74
	v_or_b32_e32 v20, v20, v74
	v_add3_u32 v128, v9, v24, s25
	v_mov_b32_e32 v9, 0x3540
	v_add_u32_e32 v151, v67, v8
	v_add_u32_e32 v8, 0, v21
	s_mov_b32 s39, 0
	v_and_b32_e32 v102, 48, v39
	v_lshlrev_b32_e32 v26, 4, v26
	v_lshlrev_b32_e32 v42, 4, v42
	v_lshlrev_b32_e32 v25, 4, v25
	v_lshlrev_b32_e32 v20, 4, v20
	v_lshlrev_b32_e32 v74, 1, v65
	v_add_lshl_u32 v22, v37, v90, 1
	v_add_lshl_u32 v11, v11, v37, 1
	v_writelane_b32 v255, s97, 32
	v_lshl_or_b32 v129, v38, 4, v9
	s_add_i32 s3, 0, 0x15c00
	s_add_i32 s88, s22, 0
	s_add_i32 s89, s23, 0
	s_add_i32 s90, s24, 0
	v_add_u32_e32 v9, 0, v66
	v_add_u32_e32 v152, 0x12800, v8
	v_mbcnt_lo_u32_b32 v8, -1, 0
	s_mov_b64 s[52:53], s[38:39]
	v_add_u32_e32 v107, s70, v89
	v_lshlrev_b32_e32 v45, 4, v45
	v_cndmask_b32_e64 v65, 0, 1.0, vcc
	v_add_u32_e32 v127, 0x2d00, v103
	v_writelane_b32 v255, s29, 44
	v_or_b32_e32 v130, 0x3500, v102
	v_add_u32_e32 v131, v28, v68
	v_add_u32_e32 v132, v28, v26
	v_add_u32_e32 v133, v29, v42
	v_add_u32_e32 v134, v29, v69
	v_add_u32_e32 v135, s3, v70
	v_add_u32_e32 v136, s3, v71
	s_mov_b32 s86, 0x4038aa3b
	s_add_i32 s67, 0, 0x10000
	v_add_u32_e32 v137, v28, v72
	v_add_u32_e32 v138, v28, v25
	v_add_u32_e32 v139, v29, v75
	v_add_u32_e32 v140, v29, v20
	v_add_u32_e32 v141, s3, v73
	v_add_u32_e32 v142, s3, v74
	v_add_u32_e32 v143, v32, v33
	v_add_u32_e32 v145, v34, v35
	s_mov_b32 s87, 0xbfb8aa3b
	v_add_u32_e32 v146, v36, v44
	s_add_i32 s88, s88, 0x23900
	s_add_i32 s89, s89, 0x23900
	s_add_i32 s90, s90, 0x23900
	s_add_i32 s91, 0, 0x27900
	s_add_i32 s92, s81, 0x400
	s_add_i32 s93, s81, 0x800
	s_add_i32 s94, s81, 0xc00
	s_add_i32 s95, s81, 0x1400
	s_add_i32 s96, s81, 0x1800
	s_add_i32 s97, s81, 0x1c00
	s_add_i32 s3, 0, 0x16100
	s_add_i32 s69, 0, 0x18500
	v_mov_b32_e32 v147, 0xbf92477c
	v_add_u32_e32 v148, v40, v27
	s_xor_b64 s[54:55], s[26:27], -1
	v_add_u32_e32 v149, 0, v43
	v_add_u32_e32 v150, 0x12400, v9
	v_mov_b32_e32 v153, 0x3a27c5ac
	v_mbcnt_hi_u32_b32 v144, -1, v8
	v_add_u32_e32 v154, s71, v22
	v_add_u32_e32 v155, s71, v23
	v_add_u32_e32 v156, s71, v11
	s_mov_b32 s33, s28
	s_mov_b32 s29, 0
	v_add_u32_e32 v213, s67, v109
	v_and_b32_e32 v241, 64, v144
	v_or_b32_e32 v240, v102, v241
	v_add_u32_e32 v227, s67, v115
	v_add_u32_e32 v238, s69, v122
	v_add_u32_e32 v211, v93, v45
	v_add_u32_e32 v233, s67, v119
	v_add_u32_e32 v218, v96, v112
	v_add_u32_e32 v229, s3, v117
	v_xor_b32_e32 v243, 32, v144
	v_add_u32_e32 v21, 64, v241
	v_cmp_lt_i32_e32 vcc, v243, v21
	s_nop 1
	v_cndmask_b32_e32 v20, v144, v243, vcc
	v_lshlrev_b32_e32 v222, 2, v20
	v_add_u32_e32 v228, s67, v116
	v_add_u32_e32 v231, s3, v118
	v_add_u32_e32 v234, s67, v120
	v_add_u32_e32 v208, v94, v108
	v_add_u32_e32 v232, s69, v118
	v_add_u32_e32 v235, s3, v121
	v_add_u32_e32 v210, v96, v108
	v_add_u32_e32 v209, v95, v108
	v_add_u32_e32 v224, s71, v114
	v_add_u32_e32 v216, v94, v112
	v_add_u32_e32 v239, 0x12600, v97
	v_add_u32_e32 v223, s67, v113
	v_add_u32_e32 v215, v92, v111
	v_add_u32_e32 v226, s83, v102
	v_add_u32_e32 v237, s3, v122
	v_add_u32_e32 v220, v91, v111
	v_add_u32_e32 v214, s71, v110
	v_add_u32_e32 v212, v91, v45
	v_xor_b32_e32 v242, 16, v144
	v_add_u32_e32 v219, v93, v111
	v_cmp_lt_i32_e32 vcc, v242, v21
	s_nop 1
	v_cndmask_b32_e32 v22, v144, v242, vcc
	v_lshlrev_b32_e32 v221, 2, v22
	v_add_u32_e32 v225, 0x15d80, v44
	v_add_u32_e32 v217, v95, v112
	v_add_u32_e32 v236, s69, v121
	v_add_u32_e32 v230, s69, v117
	v_add_u32_e32 v207, v92, v45
	s_waitcnt vmcnt(0)

.LBB0_645:
	v_readlane_b32 s12, v255, 0
	v_or_b32_e32 v130, s54, v143
	v_lshl_or_b32 v131, v142, 11, s55
	s_lshl_b32 s10, s20, 9
	v_readlane_b32 s13, v255, 1
	v_readlane_b32 s14, v255, 2
	v_readlane_b32 s15, v255, 3
	v_readlane_b32 s16, v255, 4
	v_readlane_b32 s17, v255, 5
	v_or_b32_e32 v128, v131, v130
	s_or_b32 s10, s21, s10
	v_readlane_b32 s18, v255, 6
	v_readlane_b32 s19, v255, 7
	s_mov_b64 s[12:13], s[16:17]
	v_add_u32_e32 v128, s10, v128
	s_mov_b64 s[14:15], s[18:19]
	v_mov_b32_e32 v220, v128
	v_add_u32_e32 v221, 0x8000, v128
	v_add_u32_e32 v222, 0x10000, v128
	v_add_u32_e32 v223, 0x18000, v128
	v_add_u32_e32 v224, 0x40000, v128
	v_add_u32_e32 v225, 0x48000, v128
	v_add_u32_e32 v226, 0x50000, v128
	v_add_u32_e32 v227, 0x58000, v128
	global_load_dwordx4 v[156:159], v220, s[24:25]
	global_load_dwordx4 v[160:163], v220, s[14:15]
	global_load_dwordx4 v[164:167], v220, s[24:25] offset:256
	global_load_dwordx4 v[168:171], v220, s[14:15] offset:256
	global_load_dwordx4 v[172:175], v221, s[24:25]
	global_load_dwordx4 v[176:179], v221, s[14:15]
	global_load_dwordx4 v[180:183], v221, s[24:25] offset:256
	global_load_dwordx4 v[184:187], v221, s[14:15] offset:256
	global_load_dwordx4 v[188:191], v222, s[24:25]
	global_load_dwordx4 v[192:195], v222, s[14:15]
	global_load_dwordx4 v[196:199], v222, s[24:25] offset:256
	global_load_dwordx4 v[200:203], v222, s[14:15] offset:256
	global_load_dwordx4 v[204:207], v223, s[24:25]
	global_load_dwordx4 v[208:211], v223, s[14:15]
	global_load_dwordx4 v[212:215], v223, s[24:25] offset:256
	global_load_dwordx4 v[216:219], v223, s[14:15] offset:256
	s_waitcnt vmcnt(14)
	v_cvt_f32_f16_e32 v228, v156
	v_cvt_f32_f16_sdwa v229, v156 dst_sel:DWORD dst_unused:UNUSED_PAD src0_sel:WORD_1
	v_cvt_f32_f16_e32 v230, v157
	v_cvt_f32_f16_sdwa v231, v157 dst_sel:DWORD dst_unused:UNUSED_PAD src0_sel:WORD_1
	v_cvt_f32_f16_e32 v232, v158
	v_cvt_f32_f16_sdwa v233, v158 dst_sel:DWORD dst_unused:UNUSED_PAD src0_sel:WORD_1
	v_cvt_f32_f16_e32 v234, v159
	v_cvt_f32_f16_sdwa v235, v159 dst_sel:DWORD dst_unused:UNUSED_PAD src0_sel:WORD_1
	v_cvt_f32_f16_e32 v236, v160
	v_cvt_f32_f16_sdwa v237, v160 dst_sel:DWORD dst_unused:UNUSED_PAD src0_sel:WORD_1
	v_cvt_f32_f16_e32 v238, v161
	v_cvt_f32_f16_sdwa v239, v161 dst_sel:DWORD dst_unused:UNUSED_PAD src0_sel:WORD_1
	v_cvt_f32_f16_e32 v240, v162
	v_cvt_f32_f16_sdwa v241, v162 dst_sel:DWORD dst_unused:UNUSED_PAD src0_sel:WORD_1
	v_cvt_f32_f16_e32 v242, v163
	v_cvt_f32_f16_sdwa v243, v163 dst_sel:DWORD dst_unused:UNUSED_PAD src0_sel:WORD_1
	v_pk_fma_f32 v[124:125], v[124:125], v[236:237], v[228:229]
	v_pk_fma_f32 v[126:127], v[126:127], v[238:239], v[230:231]
	v_pk_fma_f32 v[120:121], v[120:121], v[240:241], v[232:233]
	v_pk_fma_f32 v[122:123], v[122:123], v[242:243], v[234:235]
	v_cvt_pk_f16_f32 v156, v124, v125
	v_cvt_pk_f16_f32 v157, v126, v127
	v_cvt_pk_f16_f32 v158, v120, v121
	v_cvt_pk_f16_f32 v159, v122, v123
	global_store_dwordx4 v220, v[156:159], s[22:23] sc1
	s_nop 1
	global_load_dwordx4 v[156:159], v224, s[24:25]
	global_load_dwordx4 v[160:163], v224, s[14:15]
	s_waitcnt vmcnt(15)
	v_cvt_f32_f16_e32 v228, v164
	v_cvt_f32_f16_sdwa v229, v164 dst_sel:DWORD dst_unused:UNUSED_PAD src0_sel:WORD_1
	v_cvt_f32_f16_e32 v230, v165
	v_cvt_f32_f16_sdwa v231, v165 dst_sel:DWORD dst_unused:UNUSED_PAD src0_sel:WORD_1
	v_cvt_f32_f16_e32 v232, v166
	v_cvt_f32_f16_sdwa v233, v166 dst_sel:DWORD dst_unused:UNUSED_PAD src0_sel:WORD_1
	v_cvt_f32_f16_e32 v234, v167
	v_cvt_f32_f16_sdwa v235, v167 dst_sel:DWORD dst_unused:UNUSED_PAD src0_sel:WORD_1
	v_cvt_f32_f16_e32 v236, v168
	v_cvt_f32_f16_sdwa v237, v168 dst_sel:DWORD dst_unused:UNUSED_PAD src0_sel:WORD_1
	v_cvt_f32_f16_e32 v238, v169
	v_cvt_f32_f16_sdwa v239, v169 dst_sel:DWORD dst_unused:UNUSED_PAD src0_sel:WORD_1
	v_cvt_f32_f16_e32 v240, v170
	v_cvt_f32_f16_sdwa v241, v170 dst_sel:DWORD dst_unused:UNUSED_PAD src0_sel:WORD_1
	v_cvt_f32_f16_e32 v242, v171
	v_cvt_f32_f16_sdwa v243, v171 dst_sel:DWORD dst_unused:UNUSED_PAD src0_sel:WORD_1
	v_pk_fma_f32 v[116:117], v[116:117], v[236:237], v[228:229]
	v_pk_fma_f32 v[118:119], v[118:119], v[238:239], v[230:231]
	v_pk_fma_f32 v[112:113], v[112:113], v[240:241], v[232:233]
	v_pk_fma_f32 v[114:115], v[114:115], v[242:243], v[234:235]
	v_cvt_pk_f16_f32 v164, v116, v117
	v_cvt_pk_f16_f32 v165, v118, v119
	v_cvt_pk_f16_f32 v166, v112, v113
	v_cvt_pk_f16_f32 v167, v114, v115
	global_store_dwordx4 v220, v[164:167], s[22:23] offset:256 sc1
	s_nop 1
	global_load_dwordx4 v[164:167], v224, s[24:25] offset:256
	global_load_dwordx4 v[168:171], v224, s[14:15] offset:256
	s_waitcnt vmcnt(16)
	v_cvt_f32_f16_e32 v228, v172
	v_cvt_f32_f16_sdwa v229, v172 dst_sel:DWORD dst_unused:UNUSED_PAD src0_sel:WORD_1
	v_cvt_f32_f16_e32 v230, v173
	v_cvt_f32_f16_sdwa v231, v173 dst_sel:DWORD dst_unused:UNUSED_PAD src0_sel:WORD_1
	v_cvt_f32_f16_e32 v232, v174
	v_cvt_f32_f16_sdwa v233, v174 dst_sel:DWORD dst_unused:UNUSED_PAD src0_sel:WORD_1
	v_cvt_f32_f16_e32 v234, v175
	v_cvt_f32_f16_sdwa v235, v175 dst_sel:DWORD dst_unused:UNUSED_PAD src0_sel:WORD_1
	v_cvt_f32_f16_e32 v236, v176
	v_cvt_f32_f16_sdwa v237, v176 dst_sel:DWORD dst_unused:UNUSED_PAD src0_sel:WORD_1
	v_cvt_f32_f16_e32 v238, v177
	v_cvt_f32_f16_sdwa v239, v177 dst_sel:DWORD dst_unused:UNUSED_PAD src0_sel:WORD_1
	v_cvt_f32_f16_e32 v240, v178
	v_cvt_f32_f16_sdwa v241, v178 dst_sel:DWORD dst_unused:UNUSED_PAD src0_sel:WORD_1
	v_cvt_f32_f16_e32 v242, v179
	v_cvt_f32_f16_sdwa v243, v179 dst_sel:DWORD dst_unused:UNUSED_PAD src0_sel:WORD_1
	v_pk_fma_f32 v[108:109], v[108:109], v[236:237], v[228:229]
	v_pk_fma_f32 v[110:111], v[110:111], v[238:239], v[230:231]
	v_pk_fma_f32 v[104:105], v[104:105], v[240:241], v[232:233]
	v_pk_fma_f32 v[106:107], v[106:107], v[242:243], v[234:235]
	v_cvt_pk_f16_f32 v172, v108, v109
	v_cvt_pk_f16_f32 v173, v110, v111
	v_cvt_pk_f16_f32 v174, v104, v105
	v_cvt_pk_f16_f32 v175, v106, v107
	global_store_dwordx4 v221, v[172:175], s[22:23] sc1
	s_nop 1
	global_load_dwordx4 v[172:175], v225, s[24:25]
	global_load_dwordx4 v[176:179], v225, s[14:15]
	s_waitcnt vmcnt(17)
	v_cvt_f32_f16_e32 v228, v180
	v_cvt_f32_f16_sdwa v229, v180 dst_sel:DWORD dst_unused:UNUSED_PAD src0_sel:WORD_1
	v_cvt_f32_f16_e32 v230, v181
	v_cvt_f32_f16_sdwa v231, v181 dst_sel:DWORD dst_unused:UNUSED_PAD src0_sel:WORD_1
	v_cvt_f32_f16_e32 v232, v182
	v_cvt_f32_f16_sdwa v233, v182 dst_sel:DWORD dst_unused:UNUSED_PAD src0_sel:WORD_1
	v_cvt_f32_f16_e32 v234, v183
	v_cvt_f32_f16_sdwa v235, v183 dst_sel:DWORD dst_unused:UNUSED_PAD src0_sel:WORD_1
	v_cvt_f32_f16_e32 v236, v184
	v_cvt_f32_f16_sdwa v237, v184 dst_sel:DWORD dst_unused:UNUSED_PAD src0_sel:WORD_1
	v_cvt_f32_f16_e32 v238, v185
	v_cvt_f32_f16_sdwa v239, v185 dst_sel:DWORD dst_unused:UNUSED_PAD src0_sel:WORD_1
	v_cvt_f32_f16_e32 v240, v186
	v_cvt_f32_f16_sdwa v241, v186 dst_sel:DWORD dst_unused:UNUSED_PAD src0_sel:WORD_1
	v_cvt_f32_f16_e32 v242, v187
	v_cvt_f32_f16_sdwa v243, v187 dst_sel:DWORD dst_unused:UNUSED_PAD src0_sel:WORD_1
	v_pk_fma_f32 v[100:101], v[100:101], v[236:237], v[228:229]
	v_pk_fma_f32 v[102:103], v[102:103], v[238:239], v[230:231]
	v_pk_fma_f32 v[96:97], v[96:97], v[240:241], v[232:233]
	v_pk_fma_f32 v[98:99], v[98:99], v[242:243], v[234:235]
	v_cvt_pk_f16_f32 v180, v100, v101
	v_cvt_pk_f16_f32 v181, v102, v103
	v_cvt_pk_f16_f32 v182, v96, v97
	v_cvt_pk_f16_f32 v183, v98, v99
	global_store_dwordx4 v221, v[180:183], s[22:23] offset:256 sc1
	s_nop 1
	global_load_dwordx4 v[180:183], v225, s[24:25] offset:256
	global_load_dwordx4 v[184:187], v225, s[14:15] offset:256
	s_waitcnt vmcnt(18)
	v_cvt_f32_f16_e32 v228, v188
	v_cvt_f32_f16_sdwa v229, v188 dst_sel:DWORD dst_unused:UNUSED_PAD src0_sel:WORD_1
	v_cvt_f32_f16_e32 v230, v189
	v_cvt_f32_f16_sdwa v231, v189 dst_sel:DWORD dst_unused:UNUSED_PAD src0_sel:WORD_1
	v_cvt_f32_f16_e32 v232, v190
	v_cvt_f32_f16_sdwa v233, v190 dst_sel:DWORD dst_unused:UNUSED_PAD src0_sel:WORD_1
	v_cvt_f32_f16_e32 v234, v191
	v_cvt_f32_f16_sdwa v235, v191 dst_sel:DWORD dst_unused:UNUSED_PAD src0_sel:WORD_1
	v_cvt_f32_f16_e32 v236, v192
	v_cvt_f32_f16_sdwa v237, v192 dst_sel:DWORD dst_unused:UNUSED_PAD src0_sel:WORD_1
	v_cvt_f32_f16_e32 v238, v193
	v_cvt_f32_f16_sdwa v239, v193 dst_sel:DWORD dst_unused:UNUSED_PAD src0_sel:WORD_1
	v_cvt_f32_f16_e32 v240, v194
	v_cvt_f32_f16_sdwa v241, v194 dst_sel:DWORD dst_unused:UNUSED_PAD src0_sel:WORD_1
	v_cvt_f32_f16_e32 v242, v195
	v_cvt_f32_f16_sdwa v243, v195 dst_sel:DWORD dst_unused:UNUSED_PAD src0_sel:WORD_1
	v_pk_fma_f32 v[92:93], v[92:93], v[236:237], v[228:229]
	v_pk_fma_f32 v[94:95], v[94:95], v[238:239], v[230:231]
	v_pk_fma_f32 v[88:89], v[88:89], v[240:241], v[232:233]
	v_pk_fma_f32 v[90:91], v[90:91], v[242:243], v[234:235]
	v_cvt_pk_f16_f32 v188, v92, v93
	v_cvt_pk_f16_f32 v189, v94, v95
	v_cvt_pk_f16_f32 v190, v88, v89
	v_cvt_pk_f16_f32 v191, v90, v91
	global_store_dwordx4 v222, v[188:191], s[22:23] sc1
	s_nop 1
	global_load_dwordx4 v[188:191], v226, s[24:25]
	global_load_dwordx4 v[192:195], v226, s[14:15]
	s_waitcnt vmcnt(19)
	v_cvt_f32_f16_e32 v228, v196
	v_cvt_f32_f16_sdwa v229, v196 dst_sel:DWORD dst_unused:UNUSED_PAD src0_sel:WORD_1
	v_cvt_f32_f16_e32 v230, v197
	v_cvt_f32_f16_sdwa v231, v197 dst_sel:DWORD dst_unused:UNUSED_PAD src0_sel:WORD_1
	v_cvt_f32_f16_e32 v232, v198
	v_cvt_f32_f16_sdwa v233, v198 dst_sel:DWORD dst_unused:UNUSED_PAD src0_sel:WORD_1
	v_cvt_f32_f16_e32 v234, v199
	v_cvt_f32_f16_sdwa v235, v199 dst_sel:DWORD dst_unused:UNUSED_PAD src0_sel:WORD_1
	v_cvt_f32_f16_e32 v236, v200
	v_cvt_f32_f16_sdwa v237, v200 dst_sel:DWORD dst_unused:UNUSED_PAD src0_sel:WORD_1
	v_cvt_f32_f16_e32 v238, v201
	v_cvt_f32_f16_sdwa v239, v201 dst_sel:DWORD dst_unused:UNUSED_PAD src0_sel:WORD_1
	v_cvt_f32_f16_e32 v240, v202
	v_cvt_f32_f16_sdwa v241, v202 dst_sel:DWORD dst_unused:UNUSED_PAD src0_sel:WORD_1
	v_cvt_f32_f16_e32 v242, v203
	v_cvt_f32_f16_sdwa v243, v203 dst_sel:DWORD dst_unused:UNUSED_PAD src0_sel:WORD_1
	v_pk_fma_f32 v[84:85], v[84:85], v[236:237], v[228:229]
	v_pk_fma_f32 v[86:87], v[86:87], v[238:239], v[230:231]
	v_pk_fma_f32 v[80:81], v[80:81], v[240:241], v[232:233]
	v_pk_fma_f32 v[82:83], v[82:83], v[242:243], v[234:235]
	v_cvt_pk_f16_f32 v196, v84, v85
	v_cvt_pk_f16_f32 v197, v86, v87
	v_cvt_pk_f16_f32 v198, v80, v81
	v_cvt_pk_f16_f32 v199, v82, v83
	global_store_dwordx4 v222, v[196:199], s[22:23] offset:256 sc1
	s_nop 1
	global_load_dwordx4 v[196:199], v226, s[24:25] offset:256
	global_load_dwordx4 v[200:203], v226, s[14:15] offset:256
	s_waitcnt vmcnt(20)
	v_cvt_f32_f16_e32 v228, v204
	v_cvt_f32_f16_sdwa v229, v204 dst_sel:DWORD dst_unused:UNUSED_PAD src0_sel:WORD_1
	v_cvt_f32_f16_e32 v230, v205
	v_cvt_f32_f16_sdwa v231, v205 dst_sel:DWORD dst_unused:UNUSED_PAD src0_sel:WORD_1
	v_cvt_f32_f16_e32 v232, v206
	v_cvt_f32_f16_sdwa v233, v206 dst_sel:DWORD dst_unused:UNUSED_PAD src0_sel:WORD_1
	v_cvt_f32_f16_e32 v234, v207
	v_cvt_f32_f16_sdwa v235, v207 dst_sel:DWORD dst_unused:UNUSED_PAD src0_sel:WORD_1
	v_cvt_f32_f16_e32 v236, v208
	v_cvt_f32_f16_sdwa v237, v208 dst_sel:DWORD dst_unused:UNUSED_PAD src0_sel:WORD_1
	v_cvt_f32_f16_e32 v238, v209
	v_cvt_f32_f16_sdwa v239, v209 dst_sel:DWORD dst_unused:UNUSED_PAD src0_sel:WORD_1
	v_cvt_f32_f16_e32 v240, v210
	v_cvt_f32_f16_sdwa v241, v210 dst_sel:DWORD dst_unused:UNUSED_PAD src0_sel:WORD_1
	v_cvt_f32_f16_e32 v242, v211
	v_cvt_f32_f16_sdwa v243, v211 dst_sel:DWORD dst_unused:UNUSED_PAD src0_sel:WORD_1
	v_pk_fma_f32 v[76:77], v[76:77], v[236:237], v[228:229]
	v_pk_fma_f32 v[78:79], v[78:79], v[238:239], v[230:231]
	v_pk_fma_f32 v[72:73], v[72:73], v[240:241], v[232:233]
	v_pk_fma_f32 v[74:75], v[74:75], v[242:243], v[234:235]
	v_cvt_pk_f16_f32 v204, v76, v77
	v_cvt_pk_f16_f32 v205, v78, v79
	v_cvt_pk_f16_f32 v206, v72, v73
	v_cvt_pk_f16_f32 v207, v74, v75
	global_store_dwordx4 v223, v[204:207], s[22:23] sc1
	s_nop 1
	global_load_dwordx4 v[204:207], v227, s[24:25]
	global_load_dwordx4 v[208:211], v227, s[14:15]
	s_waitcnt vmcnt(21)
	v_cvt_f32_f16_e32 v228, v212
	v_cvt_f32_f16_sdwa v229, v212 dst_sel:DWORD dst_unused:UNUSED_PAD src0_sel:WORD_1
	v_cvt_f32_f16_e32 v230, v213
	v_cvt_f32_f16_sdwa v231, v213 dst_sel:DWORD dst_unused:UNUSED_PAD src0_sel:WORD_1
	v_cvt_f32_f16_e32 v232, v214
	v_cvt_f32_f16_sdwa v233, v214 dst_sel:DWORD dst_unused:UNUSED_PAD src0_sel:WORD_1
	v_cvt_f32_f16_e32 v234, v215
	v_cvt_f32_f16_sdwa v235, v215 dst_sel:DWORD dst_unused:UNUSED_PAD src0_sel:WORD_1
	v_cvt_f32_f16_e32 v236, v216
	v_cvt_f32_f16_sdwa v237, v216 dst_sel:DWORD dst_unused:UNUSED_PAD src0_sel:WORD_1
	v_cvt_f32_f16_e32 v238, v217
	v_cvt_f32_f16_sdwa v239, v217 dst_sel:DWORD dst_unused:UNUSED_PAD src0_sel:WORD_1
	v_cvt_f32_f16_e32 v240, v218
	v_cvt_f32_f16_sdwa v241, v218 dst_sel:DWORD dst_unused:UNUSED_PAD src0_sel:WORD_1
	v_cvt_f32_f16_e32 v242, v219
	v_cvt_f32_f16_sdwa v243, v219 dst_sel:DWORD dst_unused:UNUSED_PAD src0_sel:WORD_1
	v_pk_fma_f32 v[68:69], v[68:69], v[236:237], v[228:229]
	v_pk_fma_f32 v[70:71], v[70:71], v[238:239], v[230:231]
	v_pk_fma_f32 v[64:65], v[64:65], v[240:241], v[232:233]
	v_pk_fma_f32 v[66:67], v[66:67], v[242:243], v[234:235]
	v_cvt_pk_f16_f32 v212, v68, v69
	v_cvt_pk_f16_f32 v213, v70, v71
	v_cvt_pk_f16_f32 v214, v64, v65
	v_cvt_pk_f16_f32 v215, v66, v67
	global_store_dwordx4 v223, v[212:215], s[22:23] offset:256 sc1
	s_nop 1
	global_load_dwordx4 v[212:215], v227, s[24:25] offset:256
	global_load_dwordx4 v[216:219], v227, s[14:15] offset:256
	s_waitcnt vmcnt(21)
	v_cvt_f32_f16_e32 v228, v156
	v_cvt_f32_f16_sdwa v229, v156 dst_sel:DWORD dst_unused:UNUSED_PAD src0_sel:WORD_1
	v_cvt_f32_f16_e32 v230, v157
	v_cvt_f32_f16_sdwa v231, v157 dst_sel:DWORD dst_unused:UNUSED_PAD src0_sel:WORD_1
	v_cvt_f32_f16_e32 v232, v158
	v_cvt_f32_f16_sdwa v233, v158 dst_sel:DWORD dst_unused:UNUSED_PAD src0_sel:WORD_1
	v_cvt_f32_f16_e32 v234, v159
	v_cvt_f32_f16_sdwa v235, v159 dst_sel:DWORD dst_unused:UNUSED_PAD src0_sel:WORD_1
	v_cvt_f32_f16_e32 v236, v160
	v_cvt_f32_f16_sdwa v237, v160 dst_sel:DWORD dst_unused:UNUSED_PAD src0_sel:WORD_1
	v_cvt_f32_f16_e32 v238, v161
	v_cvt_f32_f16_sdwa v239, v161 dst_sel:DWORD dst_unused:UNUSED_PAD src0_sel:WORD_1
	v_cvt_f32_f16_e32 v240, v162
	v_cvt_f32_f16_sdwa v241, v162 dst_sel:DWORD dst_unused:UNUSED_PAD src0_sel:WORD_1
	v_cvt_f32_f16_e32 v242, v163
	v_cvt_f32_f16_sdwa v243, v163 dst_sel:DWORD dst_unused:UNUSED_PAD src0_sel:WORD_1
	v_pk_fma_f32 v[60:61], v[60:61], v[236:237], v[228:229]
	v_pk_fma_f32 v[62:63], v[62:63], v[238:239], v[230:231]
	v_pk_fma_f32 v[56:57], v[56:57], v[240:241], v[232:233]
	v_pk_fma_f32 v[58:59], v[58:59], v[242:243], v[234:235]
	v_cvt_pk_f16_f32 v156, v60, v61
	v_cvt_pk_f16_f32 v157, v62, v63
	v_cvt_pk_f16_f32 v158, v56, v57
	v_cvt_pk_f16_f32 v159, v58, v59
	global_store_dwordx4 v224, v[156:159], s[22:23] sc1
	s_nop 1
	s_waitcnt vmcnt(19)
	v_cvt_f32_f16_e32 v228, v164
	v_cvt_f32_f16_sdwa v229, v164 dst_sel:DWORD dst_unused:UNUSED_PAD src0_sel:WORD_1
	v_cvt_f32_f16_e32 v230, v165
	v_cvt_f32_f16_sdwa v231, v165 dst_sel:DWORD dst_unused:UNUSED_PAD src0_sel:WORD_1
	v_cvt_f32_f16_e32 v232, v166
	v_cvt_f32_f16_sdwa v233, v166 dst_sel:DWORD dst_unused:UNUSED_PAD src0_sel:WORD_1
	v_cvt_f32_f16_e32 v234, v167
	v_cvt_f32_f16_sdwa v235, v167 dst_sel:DWORD dst_unused:UNUSED_PAD src0_sel:WORD_1
	v_cvt_f32_f16_e32 v236, v168
	v_cvt_f32_f16_sdwa v237, v168 dst_sel:DWORD dst_unused:UNUSED_PAD src0_sel:WORD_1
	v_cvt_f32_f16_e32 v238, v169
	v_cvt_f32_f16_sdwa v239, v169 dst_sel:DWORD dst_unused:UNUSED_PAD src0_sel:WORD_1
	v_cvt_f32_f16_e32 v240, v170
	v_cvt_f32_f16_sdwa v241, v170 dst_sel:DWORD dst_unused:UNUSED_PAD src0_sel:WORD_1
	v_cvt_f32_f16_e32 v242, v171
	v_cvt_f32_f16_sdwa v243, v171 dst_sel:DWORD dst_unused:UNUSED_PAD src0_sel:WORD_1
	v_pk_fma_f32 v[52:53], v[52:53], v[236:237], v[228:229]
	v_pk_fma_f32 v[54:55], v[54:55], v[238:239], v[230:231]
	v_pk_fma_f32 v[48:49], v[48:49], v[240:241], v[232:233]
	v_pk_fma_f32 v[50:51], v[50:51], v[242:243], v[234:235]
	v_cvt_pk_f16_f32 v164, v52, v53
	v_cvt_pk_f16_f32 v165, v54, v55
	v_cvt_pk_f16_f32 v166, v48, v49
	v_cvt_pk_f16_f32 v167, v50, v51
	global_store_dwordx4 v224, v[164:167], s[22:23] offset:256 sc1
	s_nop 1
	s_waitcnt vmcnt(17)
	v_cvt_f32_f16_e32 v228, v172
	v_cvt_f32_f16_sdwa v229, v172 dst_sel:DWORD dst_unused:UNUSED_PAD src0_sel:WORD_1
	v_cvt_f32_f16_e32 v230, v173
	v_cvt_f32_f16_sdwa v231, v173 dst_sel:DWORD dst_unused:UNUSED_PAD src0_sel:WORD_1
	v_cvt_f32_f16_e32 v232, v174
	v_cvt_f32_f16_sdwa v233, v174 dst_sel:DWORD dst_unused:UNUSED_PAD src0_sel:WORD_1
	v_cvt_f32_f16_e32 v234, v175
	v_cvt_f32_f16_sdwa v235, v175 dst_sel:DWORD dst_unused:UNUSED_PAD src0_sel:WORD_1
	v_cvt_f32_f16_e32 v236, v176
	v_cvt_f32_f16_sdwa v237, v176 dst_sel:DWORD dst_unused:UNUSED_PAD src0_sel:WORD_1
	v_cvt_f32_f16_e32 v238, v177
	v_cvt_f32_f16_sdwa v239, v177 dst_sel:DWORD dst_unused:UNUSED_PAD src0_sel:WORD_1
	v_cvt_f32_f16_e32 v240, v178
	v_cvt_f32_f16_sdwa v241, v178 dst_sel:DWORD dst_unused:UNUSED_PAD src0_sel:WORD_1
	v_cvt_f32_f16_e32 v242, v179
	v_cvt_f32_f16_sdwa v243, v179 dst_sel:DWORD dst_unused:UNUSED_PAD src0_sel:WORD_1
	v_pk_fma_f32 v[44:45], v[44:45], v[236:237], v[228:229]
	v_pk_fma_f32 v[46:47], v[46:47], v[238:239], v[230:231]
	v_pk_fma_f32 v[40:41], v[40:41], v[240:241], v[232:233]
	v_pk_fma_f32 v[42:43], v[42:43], v[242:243], v[234:235]
	v_cvt_pk_f16_f32 v172, v44, v45
	v_cvt_pk_f16_f32 v173, v46, v47
	v_cvt_pk_f16_f32 v174, v40, v41
	v_cvt_pk_f16_f32 v175, v42, v43
	global_store_dwordx4 v225, v[172:175], s[22:23] sc1
	s_nop 1
	s_waitcnt vmcnt(15)
	v_cvt_f32_f16_e32 v228, v180
	v_cvt_f32_f16_sdwa v229, v180 dst_sel:DWORD dst_unused:UNUSED_PAD src0_sel:WORD_1
	v_cvt_f32_f16_e32 v230, v181
	v_cvt_f32_f16_sdwa v231, v181 dst_sel:DWORD dst_unused:UNUSED_PAD src0_sel:WORD_1
	v_cvt_f32_f16_e32 v232, v182
	v_cvt_f32_f16_sdwa v233, v182 dst_sel:DWORD dst_unused:UNUSED_PAD src0_sel:WORD_1
	v_cvt_f32_f16_e32 v234, v183
	v_cvt_f32_f16_sdwa v235, v183 dst_sel:DWORD dst_unused:UNUSED_PAD src0_sel:WORD_1
	v_cvt_f32_f16_e32 v236, v184
	v_cvt_f32_f16_sdwa v237, v184 dst_sel:DWORD dst_unused:UNUSED_PAD src0_sel:WORD_1
	v_cvt_f32_f16_e32 v238, v185
	v_cvt_f32_f16_sdwa v239, v185 dst_sel:DWORD dst_unused:UNUSED_PAD src0_sel:WORD_1
	v_cvt_f32_f16_e32 v240, v186
	v_cvt_f32_f16_sdwa v241, v186 dst_sel:DWORD dst_unused:UNUSED_PAD src0_sel:WORD_1
	v_cvt_f32_f16_e32 v242, v187
	v_cvt_f32_f16_sdwa v243, v187 dst_sel:DWORD dst_unused:UNUSED_PAD src0_sel:WORD_1
	v_pk_fma_f32 v[36:37], v[36:37], v[236:237], v[228:229]
	v_pk_fma_f32 v[38:39], v[38:39], v[238:239], v[230:231]
	v_pk_fma_f32 v[32:33], v[32:33], v[240:241], v[232:233]
	v_pk_fma_f32 v[34:35], v[34:35], v[242:243], v[234:235]
	v_cvt_pk_f16_f32 v180, v36, v37
	v_cvt_pk_f16_f32 v181, v38, v39
	v_cvt_pk_f16_f32 v182, v32, v33
	v_cvt_pk_f16_f32 v183, v34, v35
	global_store_dwordx4 v225, v[180:183], s[22:23] offset:256 sc1
	s_nop 1
	s_waitcnt vmcnt(13)
	v_cvt_f32_f16_e32 v228, v188
	v_cvt_f32_f16_sdwa v229, v188 dst_sel:DWORD dst_unused:UNUSED_PAD src0_sel:WORD_1
	v_cvt_f32_f16_e32 v230, v189
	v_cvt_f32_f16_sdwa v231, v189 dst_sel:DWORD dst_unused:UNUSED_PAD src0_sel:WORD_1
	v_cvt_f32_f16_e32 v232, v190
	v_cvt_f32_f16_sdwa v233, v190 dst_sel:DWORD dst_unused:UNUSED_PAD src0_sel:WORD_1
	v_cvt_f32_f16_e32 v234, v191
	v_cvt_f32_f16_sdwa v235, v191 dst_sel:DWORD dst_unused:UNUSED_PAD src0_sel:WORD_1
	v_cvt_f32_f16_e32 v236, v192
	v_cvt_f32_f16_sdwa v237, v192 dst_sel:DWORD dst_unused:UNUSED_PAD src0_sel:WORD_1
	v_cvt_f32_f16_e32 v238, v193
	v_cvt_f32_f16_sdwa v239, v193 dst_sel:DWORD dst_unused:UNUSED_PAD src0_sel:WORD_1
	v_cvt_f32_f16_e32 v240, v194
	v_cvt_f32_f16_sdwa v241, v194 dst_sel:DWORD dst_unused:UNUSED_PAD src0_sel:WORD_1
	v_cvt_f32_f16_e32 v242, v195
	v_cvt_f32_f16_sdwa v243, v195 dst_sel:DWORD dst_unused:UNUSED_PAD src0_sel:WORD_1
	v_pk_fma_f32 v[28:29], v[28:29], v[236:237], v[228:229]
	v_pk_fma_f32 v[30:31], v[30:31], v[238:239], v[230:231]
	v_pk_fma_f32 v[24:25], v[24:25], v[240:241], v[232:233]
	v_pk_fma_f32 v[26:27], v[26:27], v[242:243], v[234:235]
	v_cvt_pk_f16_f32 v188, v28, v29
	v_cvt_pk_f16_f32 v189, v30, v31
	v_cvt_pk_f16_f32 v190, v24, v25
	v_cvt_pk_f16_f32 v191, v26, v27
	global_store_dwordx4 v226, v[188:191], s[22:23] sc1
	s_nop 1
	s_waitcnt vmcnt(11)
	v_cvt_f32_f16_e32 v228, v196
	v_cvt_f32_f16_sdwa v229, v196 dst_sel:DWORD dst_unused:UNUSED_PAD src0_sel:WORD_1
	v_cvt_f32_f16_e32 v230, v197
	v_cvt_f32_f16_sdwa v231, v197 dst_sel:DWORD dst_unused:UNUSED_PAD src0_sel:WORD_1
	v_cvt_f32_f16_e32 v232, v198
	v_cvt_f32_f16_sdwa v233, v198 dst_sel:DWORD dst_unused:UNUSED_PAD src0_sel:WORD_1
	v_cvt_f32_f16_e32 v234, v199
	v_cvt_f32_f16_sdwa v235, v199 dst_sel:DWORD dst_unused:UNUSED_PAD src0_sel:WORD_1
	v_cvt_f32_f16_e32 v236, v200
	v_cvt_f32_f16_sdwa v237, v200 dst_sel:DWORD dst_unused:UNUSED_PAD src0_sel:WORD_1
	v_cvt_f32_f16_e32 v238, v201
	v_cvt_f32_f16_sdwa v239, v201 dst_sel:DWORD dst_unused:UNUSED_PAD src0_sel:WORD_1
	v_cvt_f32_f16_e32 v240, v202
	v_cvt_f32_f16_sdwa v241, v202 dst_sel:DWORD dst_unused:UNUSED_PAD src0_sel:WORD_1
	v_cvt_f32_f16_e32 v242, v203
	v_cvt_f32_f16_sdwa v243, v203 dst_sel:DWORD dst_unused:UNUSED_PAD src0_sel:WORD_1
	v_pk_fma_f32 v[20:21], v[20:21], v[236:237], v[228:229]
	v_pk_fma_f32 v[22:23], v[22:23], v[238:239], v[230:231]
	v_pk_fma_f32 v[16:17], v[16:17], v[240:241], v[232:233]
	v_pk_fma_f32 v[18:19], v[18:19], v[242:243], v[234:235]
	v_cvt_pk_f16_f32 v196, v20, v21
	v_cvt_pk_f16_f32 v197, v22, v23
	v_cvt_pk_f16_f32 v198, v16, v17
	v_cvt_pk_f16_f32 v199, v18, v19
	global_store_dwordx4 v226, v[196:199], s[22:23] offset:256 sc1
	s_nop 1
	s_waitcnt vmcnt(9)
	v_cvt_f32_f16_e32 v228, v204
	v_cvt_f32_f16_sdwa v229, v204 dst_sel:DWORD dst_unused:UNUSED_PAD src0_sel:WORD_1
	v_cvt_f32_f16_e32 v230, v205
	v_cvt_f32_f16_sdwa v231, v205 dst_sel:DWORD dst_unused:UNUSED_PAD src0_sel:WORD_1
	v_cvt_f32_f16_e32 v232, v206
	v_cvt_f32_f16_sdwa v233, v206 dst_sel:DWORD dst_unused:UNUSED_PAD src0_sel:WORD_1
	v_cvt_f32_f16_e32 v234, v207
	v_cvt_f32_f16_sdwa v235, v207 dst_sel:DWORD dst_unused:UNUSED_PAD src0_sel:WORD_1
	v_cvt_f32_f16_e32 v236, v208
	v_cvt_f32_f16_sdwa v237, v208 dst_sel:DWORD dst_unused:UNUSED_PAD src0_sel:WORD_1
	v_cvt_f32_f16_e32 v238, v209
	v_cvt_f32_f16_sdwa v239, v209 dst_sel:DWORD dst_unused:UNUSED_PAD src0_sel:WORD_1
	v_cvt_f32_f16_e32 v240, v210
	v_cvt_f32_f16_sdwa v241, v210 dst_sel:DWORD dst_unused:UNUSED_PAD src0_sel:WORD_1
	v_cvt_f32_f16_e32 v242, v211
	v_cvt_f32_f16_sdwa v243, v211 dst_sel:DWORD dst_unused:UNUSED_PAD src0_sel:WORD_1
	v_pk_fma_f32 v[12:13], v[12:13], v[236:237], v[228:229]
	v_pk_fma_f32 v[14:15], v[14:15], v[238:239], v[230:231]
	v_pk_fma_f32 v[8:9], v[8:9], v[240:241], v[232:233]
	v_pk_fma_f32 v[10:11], v[10:11], v[242:243], v[234:235]
	v_cvt_pk_f16_f32 v204, v12, v13
	v_cvt_pk_f16_f32 v205, v14, v15
	v_cvt_pk_f16_f32 v206, v8, v9
	v_cvt_pk_f16_f32 v207, v10, v11
	global_store_dwordx4 v227, v[204:207], s[22:23] sc1
	s_nop 1
	s_waitcnt vmcnt(7)
	v_cvt_f32_f16_e32 v228, v212
	v_cvt_f32_f16_sdwa v229, v212 dst_sel:DWORD dst_unused:UNUSED_PAD src0_sel:WORD_1
	v_cvt_f32_f16_e32 v230, v213
	v_cvt_f32_f16_sdwa v231, v213 dst_sel:DWORD dst_unused:UNUSED_PAD src0_sel:WORD_1
	v_cvt_f32_f16_e32 v232, v214
	v_cvt_f32_f16_sdwa v233, v214 dst_sel:DWORD dst_unused:UNUSED_PAD src0_sel:WORD_1
	v_cvt_f32_f16_e32 v234, v215
	v_cvt_f32_f16_sdwa v235, v215 dst_sel:DWORD dst_unused:UNUSED_PAD src0_sel:WORD_1
	v_cvt_f32_f16_e32 v236, v216
	v_cvt_f32_f16_sdwa v237, v216 dst_sel:DWORD dst_unused:UNUSED_PAD src0_sel:WORD_1
	v_cvt_f32_f16_e32 v238, v217
	v_cvt_f32_f16_sdwa v239, v217 dst_sel:DWORD dst_unused:UNUSED_PAD src0_sel:WORD_1
	v_cvt_f32_f16_e32 v240, v218
	v_cvt_f32_f16_sdwa v241, v218 dst_sel:DWORD dst_unused:UNUSED_PAD src0_sel:WORD_1
	v_cvt_f32_f16_e32 v242, v219
	v_cvt_f32_f16_sdwa v243, v219 dst_sel:DWORD dst_unused:UNUSED_PAD src0_sel:WORD_1
	v_pk_fma_f32 v[4:5], v[4:5], v[236:237], v[228:229]
	v_pk_fma_f32 v[6:7], v[6:7], v[238:239], v[230:231]
	v_pk_fma_f32 v[0:1], v[0:1], v[240:241], v[232:233]
	v_pk_fma_f32 v[2:3], v[2:3], v[242:243], v[234:235]
	v_cvt_pk_f16_f32 v212, v4, v5
	v_cvt_pk_f16_f32 v213, v6, v7
	v_cvt_pk_f16_f32 v214, v0, v1
	v_cvt_pk_f16_f32 v215, v2, v3
	global_store_dwordx4 v227, v[212:215], s[22:23] offset:256 sc1
	s_nop 1
	s_waitcnt vmcnt(0)
	s_barrier
	v_mbcnt_lo_u32_b32 v0, -1, 0
	v_mbcnt_hi_u32_b32 v0, -1, v0
	s_nop 0
	v_or_b32_e32 v0, s97, v0
	v_cmp_eq_u32_e32 vcc, 0, v0
	s_and_saveexec_b64 s[10:11], vcc
	s_cbranch_execz .LBB0_596
	s_mov_b64 s[14:15], exec
	v_mbcnt_lo_u32_b32 v0, s14, 0
	v_mbcnt_hi_u32_b32 v0, s15, v0
	v_cmp_eq_u32_e32 vcc, 0, v0
	s_and_saveexec_b64 s[12:13], vcc
	s_cbranch_execz .LBB0_648
	s_lshl_b32 s0, s0, 6
	s_lshl_b64 s[16:17], s[0:1], 2
	s_add_u32 s16, s56, s16
	s_addc_u32 s17, s57, s17
	s_bcnt1_i32_b64 s0, s[14:15]
	v_mov_b32_e32 v0, s0
	global_atomic_add v129, v0, s[16:17]

.LBB0_1235:
	v_readlane_b32 s12, v255, 0
	v_or_b32_e32 v130, s54, v143
	v_lshl_or_b32 v131, v142, 11, s55
	s_lshl_b32 s10, s20, 9
	v_readlane_b32 s13, v255, 1
	v_readlane_b32 s14, v255, 2
	v_readlane_b32 s15, v255, 3
	v_readlane_b32 s16, v255, 4
	v_readlane_b32 s17, v255, 5
	v_or_b32_e32 v128, v131, v130
	s_or_b32 s10, s21, s10
	v_readlane_b32 s18, v255, 6
	v_readlane_b32 s19, v255, 7
	s_mov_b64 s[12:13], s[16:17]
	v_add_u32_e32 v128, s10, v128
	s_mov_b64 s[14:15], s[18:19]
	v_mov_b32_e32 v220, v128
	v_add_u32_e32 v221, 0x8000, v128
	v_add_u32_e32 v222, 0x10000, v128
	v_add_u32_e32 v223, 0x18000, v128
	v_add_u32_e32 v224, 0x40000, v128
	v_add_u32_e32 v225, 0x48000, v128
	v_add_u32_e32 v226, 0x50000, v128
	v_add_u32_e32 v227, 0x58000, v128
	global_load_dwordx4 v[156:159], v220, s[24:25]
	global_load_dwordx4 v[160:163], v220, s[14:15]
	global_load_dwordx4 v[164:167], v220, s[24:25] offset:256
	global_load_dwordx4 v[168:171], v220, s[14:15] offset:256
	global_load_dwordx4 v[172:175], v221, s[24:25]
	global_load_dwordx4 v[176:179], v221, s[14:15]
	global_load_dwordx4 v[180:183], v221, s[24:25] offset:256
	global_load_dwordx4 v[184:187], v221, s[14:15] offset:256
	global_load_dwordx4 v[188:191], v222, s[24:25]
	global_load_dwordx4 v[192:195], v222, s[14:15]
	global_load_dwordx4 v[196:199], v222, s[24:25] offset:256
	global_load_dwordx4 v[200:203], v222, s[14:15] offset:256
	global_load_dwordx4 v[204:207], v223, s[24:25]
	global_load_dwordx4 v[208:211], v223, s[14:15]
	global_load_dwordx4 v[212:215], v223, s[24:25] offset:256
	global_load_dwordx4 v[216:219], v223, s[14:15] offset:256
	s_waitcnt vmcnt(14)
	v_cvt_f32_f16_e32 v228, v156
	v_cvt_f32_f16_sdwa v229, v156 dst_sel:DWORD dst_unused:UNUSED_PAD src0_sel:WORD_1
	v_cvt_f32_f16_e32 v230, v157
	v_cvt_f32_f16_sdwa v231, v157 dst_sel:DWORD dst_unused:UNUSED_PAD src0_sel:WORD_1
	v_cvt_f32_f16_e32 v232, v158
	v_cvt_f32_f16_sdwa v233, v158 dst_sel:DWORD dst_unused:UNUSED_PAD src0_sel:WORD_1
	v_cvt_f32_f16_e32 v234, v159
	v_cvt_f32_f16_sdwa v235, v159 dst_sel:DWORD dst_unused:UNUSED_PAD src0_sel:WORD_1
	v_cvt_f32_f16_e32 v236, v160
	v_cvt_f32_f16_sdwa v237, v160 dst_sel:DWORD dst_unused:UNUSED_PAD src0_sel:WORD_1
	v_cvt_f32_f16_e32 v238, v161
	v_cvt_f32_f16_sdwa v239, v161 dst_sel:DWORD dst_unused:UNUSED_PAD src0_sel:WORD_1
	v_cvt_f32_f16_e32 v240, v162
	v_cvt_f32_f16_sdwa v241, v162 dst_sel:DWORD dst_unused:UNUSED_PAD src0_sel:WORD_1
	v_cvt_f32_f16_e32 v242, v163
	v_cvt_f32_f16_sdwa v243, v163 dst_sel:DWORD dst_unused:UNUSED_PAD src0_sel:WORD_1
	v_pk_fma_f32 v[124:125], v[124:125], v[236:237], v[228:229]
	v_pk_fma_f32 v[126:127], v[126:127], v[238:239], v[230:231]
	v_pk_fma_f32 v[120:121], v[120:121], v[240:241], v[232:233]
	v_pk_fma_f32 v[122:123], v[122:123], v[242:243], v[234:235]
	v_cvt_pk_f16_f32 v156, v124, v125
	v_cvt_pk_f16_f32 v157, v126, v127
	v_cvt_pk_f16_f32 v158, v120, v121
	v_cvt_pk_f16_f32 v159, v122, v123
	global_store_dwordx4 v220, v[156:159], s[22:23] sc1
	s_nop 1
	global_load_dwordx4 v[156:159], v224, s[24:25]
	global_load_dwordx4 v[160:163], v224, s[14:15]
	s_waitcnt vmcnt(15)
	v_cvt_f32_f16_e32 v228, v164
	v_cvt_f32_f16_sdwa v229, v164 dst_sel:DWORD dst_unused:UNUSED_PAD src0_sel:WORD_1
	v_cvt_f32_f16_e32 v230, v165
	v_cvt_f32_f16_sdwa v231, v165 dst_sel:DWORD dst_unused:UNUSED_PAD src0_sel:WORD_1
	v_cvt_f32_f16_e32 v232, v166
	v_cvt_f32_f16_sdwa v233, v166 dst_sel:DWORD dst_unused:UNUSED_PAD src0_sel:WORD_1
	v_cvt_f32_f16_e32 v234, v167
	v_cvt_f32_f16_sdwa v235, v167 dst_sel:DWORD dst_unused:UNUSED_PAD src0_sel:WORD_1
	v_cvt_f32_f16_e32 v236, v168
	v_cvt_f32_f16_sdwa v237, v168 dst_sel:DWORD dst_unused:UNUSED_PAD src0_sel:WORD_1
	v_cvt_f32_f16_e32 v238, v169
	v_cvt_f32_f16_sdwa v239, v169 dst_sel:DWORD dst_unused:UNUSED_PAD src0_sel:WORD_1
	v_cvt_f32_f16_e32 v240, v170
	v_cvt_f32_f16_sdwa v241, v170 dst_sel:DWORD dst_unused:UNUSED_PAD src0_sel:WORD_1
	v_cvt_f32_f16_e32 v242, v171
	v_cvt_f32_f16_sdwa v243, v171 dst_sel:DWORD dst_unused:UNUSED_PAD src0_sel:WORD_1
	v_pk_fma_f32 v[116:117], v[116:117], v[236:237], v[228:229]
	v_pk_fma_f32 v[118:119], v[118:119], v[238:239], v[230:231]
	v_pk_fma_f32 v[112:113], v[112:113], v[240:241], v[232:233]
	v_pk_fma_f32 v[114:115], v[114:115], v[242:243], v[234:235]
	v_cvt_pk_f16_f32 v164, v116, v117
	v_cvt_pk_f16_f32 v165, v118, v119
	v_cvt_pk_f16_f32 v166, v112, v113
	v_cvt_pk_f16_f32 v167, v114, v115
	global_store_dwordx4 v220, v[164:167], s[22:23] offset:256 sc1
	s_nop 1
	global_load_dwordx4 v[164:167], v224, s[24:25] offset:256
	global_load_dwordx4 v[168:171], v224, s[14:15] offset:256
	s_waitcnt vmcnt(16)
	v_cvt_f32_f16_e32 v228, v172
	v_cvt_f32_f16_sdwa v229, v172 dst_sel:DWORD dst_unused:UNUSED_PAD src0_sel:WORD_1
	v_cvt_f32_f16_e32 v230, v173
	v_cvt_f32_f16_sdwa v231, v173 dst_sel:DWORD dst_unused:UNUSED_PAD src0_sel:WORD_1
	v_cvt_f32_f16_e32 v232, v174
	v_cvt_f32_f16_sdwa v233, v174 dst_sel:DWORD dst_unused:UNUSED_PAD src0_sel:WORD_1
	v_cvt_f32_f16_e32 v234, v175
	v_cvt_f32_f16_sdwa v235, v175 dst_sel:DWORD dst_unused:UNUSED_PAD src0_sel:WORD_1
	v_cvt_f32_f16_e32 v236, v176
	v_cvt_f32_f16_sdwa v237, v176 dst_sel:DWORD dst_unused:UNUSED_PAD src0_sel:WORD_1
	v_cvt_f32_f16_e32 v238, v177
	v_cvt_f32_f16_sdwa v239, v177 dst_sel:DWORD dst_unused:UNUSED_PAD src0_sel:WORD_1
	v_cvt_f32_f16_e32 v240, v178
	v_cvt_f32_f16_sdwa v241, v178 dst_sel:DWORD dst_unused:UNUSED_PAD src0_sel:WORD_1
	v_cvt_f32_f16_e32 v242, v179
	v_cvt_f32_f16_sdwa v243, v179 dst_sel:DWORD dst_unused:UNUSED_PAD src0_sel:WORD_1
	v_pk_fma_f32 v[108:109], v[108:109], v[236:237], v[228:229]
	v_pk_fma_f32 v[110:111], v[110:111], v[238:239], v[230:231]
	v_pk_fma_f32 v[104:105], v[104:105], v[240:241], v[232:233]
	v_pk_fma_f32 v[106:107], v[106:107], v[242:243], v[234:235]
	v_cvt_pk_f16_f32 v172, v108, v109
	v_cvt_pk_f16_f32 v173, v110, v111
	v_cvt_pk_f16_f32 v174, v104, v105
	v_cvt_pk_f16_f32 v175, v106, v107
	global_store_dwordx4 v221, v[172:175], s[22:23] sc1
	s_nop 1
	global_load_dwordx4 v[172:175], v225, s[24:25]
	global_load_dwordx4 v[176:179], v225, s[14:15]
	s_waitcnt vmcnt(17)
	v_cvt_f32_f16_e32 v228, v180
	v_cvt_f32_f16_sdwa v229, v180 dst_sel:DWORD dst_unused:UNUSED_PAD src0_sel:WORD_1
	v_cvt_f32_f16_e32 v230, v181
	v_cvt_f32_f16_sdwa v231, v181 dst_sel:DWORD dst_unused:UNUSED_PAD src0_sel:WORD_1
	v_cvt_f32_f16_e32 v232, v182
	v_cvt_f32_f16_sdwa v233, v182 dst_sel:DWORD dst_unused:UNUSED_PAD src0_sel:WORD_1
	v_cvt_f32_f16_e32 v234, v183
	v_cvt_f32_f16_sdwa v235, v183 dst_sel:DWORD dst_unused:UNUSED_PAD src0_sel:WORD_1
	v_cvt_f32_f16_e32 v236, v184
	v_cvt_f32_f16_sdwa v237, v184 dst_sel:DWORD dst_unused:UNUSED_PAD src0_sel:WORD_1
	v_cvt_f32_f16_e32 v238, v185
	v_cvt_f32_f16_sdwa v239, v185 dst_sel:DWORD dst_unused:UNUSED_PAD src0_sel:WORD_1
	v_cvt_f32_f16_e32 v240, v186
	v_cvt_f32_f16_sdwa v241, v186 dst_sel:DWORD dst_unused:UNUSED_PAD src0_sel:WORD_1
	v_cvt_f32_f16_e32 v242, v187
	v_cvt_f32_f16_sdwa v243, v187 dst_sel:DWORD dst_unused:UNUSED_PAD src0_sel:WORD_1
	v_pk_fma_f32 v[100:101], v[100:101], v[236:237], v[228:229]
	v_pk_fma_f32 v[102:103], v[102:103], v[238:239], v[230:231]
	v_pk_fma_f32 v[96:97], v[96:97], v[240:241], v[232:233]
	v_pk_fma_f32 v[98:99], v[98:99], v[242:243], v[234:235]
	v_cvt_pk_f16_f32 v180, v100, v101
	v_cvt_pk_f16_f32 v181, v102, v103
	v_cvt_pk_f16_f32 v182, v96, v97
	v_cvt_pk_f16_f32 v183, v98, v99
	global_store_dwordx4 v221, v[180:183], s[22:23] offset:256 sc1
	s_nop 1
	global_load_dwordx4 v[180:183], v225, s[24:25] offset:256
	global_load_dwordx4 v[184:187], v225, s[14:15] offset:256
	s_waitcnt vmcnt(18)
	v_cvt_f32_f16_e32 v228, v188
	v_cvt_f32_f16_sdwa v229, v188 dst_sel:DWORD dst_unused:UNUSED_PAD src0_sel:WORD_1
	v_cvt_f32_f16_e32 v230, v189
	v_cvt_f32_f16_sdwa v231, v189 dst_sel:DWORD dst_unused:UNUSED_PAD src0_sel:WORD_1
	v_cvt_f32_f16_e32 v232, v190
	v_cvt_f32_f16_sdwa v233, v190 dst_sel:DWORD dst_unused:UNUSED_PAD src0_sel:WORD_1
	v_cvt_f32_f16_e32 v234, v191
	v_cvt_f32_f16_sdwa v235, v191 dst_sel:DWORD dst_unused:UNUSED_PAD src0_sel:WORD_1
	v_cvt_f32_f16_e32 v236, v192
	v_cvt_f32_f16_sdwa v237, v192 dst_sel:DWORD dst_unused:UNUSED_PAD src0_sel:WORD_1
	v_cvt_f32_f16_e32 v238, v193
	v_cvt_f32_f16_sdwa v239, v193 dst_sel:DWORD dst_unused:UNUSED_PAD src0_sel:WORD_1
	v_cvt_f32_f16_e32 v240, v194
	v_cvt_f32_f16_sdwa v241, v194 dst_sel:DWORD dst_unused:UNUSED_PAD src0_sel:WORD_1
	v_cvt_f32_f16_e32 v242, v195
	v_cvt_f32_f16_sdwa v243, v195 dst_sel:DWORD dst_unused:UNUSED_PAD src0_sel:WORD_1
	v_pk_fma_f32 v[92:93], v[92:93], v[236:237], v[228:229]
	v_pk_fma_f32 v[94:95], v[94:95], v[238:239], v[230:231]
	v_pk_fma_f32 v[88:89], v[88:89], v[240:241], v[232:233]
	v_pk_fma_f32 v[90:91], v[90:91], v[242:243], v[234:235]
	v_cvt_pk_f16_f32 v188, v92, v93
	v_cvt_pk_f16_f32 v189, v94, v95
	v_cvt_pk_f16_f32 v190, v88, v89
	v_cvt_pk_f16_f32 v191, v90, v91
	global_store_dwordx4 v222, v[188:191], s[22:23] sc1
	s_nop 1
	global_load_dwordx4 v[188:191], v226, s[24:25]
	global_load_dwordx4 v[192:195], v226, s[14:15]
	s_waitcnt vmcnt(19)
	v_cvt_f32_f16_e32 v228, v196
	v_cvt_f32_f16_sdwa v229, v196 dst_sel:DWORD dst_unused:UNUSED_PAD src0_sel:WORD_1
	v_cvt_f32_f16_e32 v230, v197
	v_cvt_f32_f16_sdwa v231, v197 dst_sel:DWORD dst_unused:UNUSED_PAD src0_sel:WORD_1
	v_cvt_f32_f16_e32 v232, v198
	v_cvt_f32_f16_sdwa v233, v198 dst_sel:DWORD dst_unused:UNUSED_PAD src0_sel:WORD_1
	v_cvt_f32_f16_e32 v234, v199
	v_cvt_f32_f16_sdwa v235, v199 dst_sel:DWORD dst_unused:UNUSED_PAD src0_sel:WORD_1
	v_cvt_f32_f16_e32 v236, v200
	v_cvt_f32_f16_sdwa v237, v200 dst_sel:DWORD dst_unused:UNUSED_PAD src0_sel:WORD_1
	v_cvt_f32_f16_e32 v238, v201
	v_cvt_f32_f16_sdwa v239, v201 dst_sel:DWORD dst_unused:UNUSED_PAD src0_sel:WORD_1
	v_cvt_f32_f16_e32 v240, v202
	v_cvt_f32_f16_sdwa v241, v202 dst_sel:DWORD dst_unused:UNUSED_PAD src0_sel:WORD_1
	v_cvt_f32_f16_e32 v242, v203
	v_cvt_f32_f16_sdwa v243, v203 dst_sel:DWORD dst_unused:UNUSED_PAD src0_sel:WORD_1
	v_pk_fma_f32 v[84:85], v[84:85], v[236:237], v[228:229]
	v_pk_fma_f32 v[86:87], v[86:87], v[238:239], v[230:231]
	v_pk_fma_f32 v[80:81], v[80:81], v[240:241], v[232:233]
	v_pk_fma_f32 v[82:83], v[82:83], v[242:243], v[234:235]
	v_cvt_pk_f16_f32 v196, v84, v85
	v_cvt_pk_f16_f32 v197, v86, v87
	v_cvt_pk_f16_f32 v198, v80, v81
	v_cvt_pk_f16_f32 v199, v82, v83
	global_store_dwordx4 v222, v[196:199], s[22:23] offset:256 sc1
	s_nop 1
	global_load_dwordx4 v[196:199], v226, s[24:25] offset:256
	global_load_dwordx4 v[200:203], v226, s[14:15] offset:256
	s_waitcnt vmcnt(20)
	v_cvt_f32_f16_e32 v228, v204
	v_cvt_f32_f16_sdwa v229, v204 dst_sel:DWORD dst_unused:UNUSED_PAD src0_sel:WORD_1
	v_cvt_f32_f16_e32 v230, v205
	v_cvt_f32_f16_sdwa v231, v205 dst_sel:DWORD dst_unused:UNUSED_PAD src0_sel:WORD_1
	v_cvt_f32_f16_e32 v232, v206
	v_cvt_f32_f16_sdwa v233, v206 dst_sel:DWORD dst_unused:UNUSED_PAD src0_sel:WORD_1
	v_cvt_f32_f16_e32 v234, v207
	v_cvt_f32_f16_sdwa v235, v207 dst_sel:DWORD dst_unused:UNUSED_PAD src0_sel:WORD_1
	v_cvt_f32_f16_e32 v236, v208
	v_cvt_f32_f16_sdwa v237, v208 dst_sel:DWORD dst_unused:UNUSED_PAD src0_sel:WORD_1
	v_cvt_f32_f16_e32 v238, v209
	v_cvt_f32_f16_sdwa v239, v209 dst_sel:DWORD dst_unused:UNUSED_PAD src0_sel:WORD_1
	v_cvt_f32_f16_e32 v240, v210
	v_cvt_f32_f16_sdwa v241, v210 dst_sel:DWORD dst_unused:UNUSED_PAD src0_sel:WORD_1
	v_cvt_f32_f16_e32 v242, v211
	v_cvt_f32_f16_sdwa v243, v211 dst_sel:DWORD dst_unused:UNUSED_PAD src0_sel:WORD_1
	v_pk_fma_f32 v[76:77], v[76:77], v[236:237], v[228:229]
	v_pk_fma_f32 v[78:79], v[78:79], v[238:239], v[230:231]
	v_pk_fma_f32 v[72:73], v[72:73], v[240:241], v[232:233]
	v_pk_fma_f32 v[74:75], v[74:75], v[242:243], v[234:235]
	v_cvt_pk_f16_f32 v204, v76, v77
	v_cvt_pk_f16_f32 v205, v78, v79
	v_cvt_pk_f16_f32 v206, v72, v73
	v_cvt_pk_f16_f32 v207, v74, v75
	global_store_dwordx4 v223, v[204:207], s[22:23] sc1
	s_nop 1
	global_load_dwordx4 v[204:207], v227, s[24:25]
	global_load_dwordx4 v[208:211], v227, s[14:15]
	s_waitcnt vmcnt(21)
	v_cvt_f32_f16_e32 v228, v212
	v_cvt_f32_f16_sdwa v229, v212 dst_sel:DWORD dst_unused:UNUSED_PAD src0_sel:WORD_1
	v_cvt_f32_f16_e32 v230, v213
	v_cvt_f32_f16_sdwa v231, v213 dst_sel:DWORD dst_unused:UNUSED_PAD src0_sel:WORD_1
	v_cvt_f32_f16_e32 v232, v214
	v_cvt_f32_f16_sdwa v233, v214 dst_sel:DWORD dst_unused:UNUSED_PAD src0_sel:WORD_1
	v_cvt_f32_f16_e32 v234, v215
	v_cvt_f32_f16_sdwa v235, v215 dst_sel:DWORD dst_unused:UNUSED_PAD src0_sel:WORD_1
	v_cvt_f32_f16_e32 v236, v216
	v_cvt_f32_f16_sdwa v237, v216 dst_sel:DWORD dst_unused:UNUSED_PAD src0_sel:WORD_1
	v_cvt_f32_f16_e32 v238, v217
	v_cvt_f32_f16_sdwa v239, v217 dst_sel:DWORD dst_unused:UNUSED_PAD src0_sel:WORD_1
	v_cvt_f32_f16_e32 v240, v218
	v_cvt_f32_f16_sdwa v241, v218 dst_sel:DWORD dst_unused:UNUSED_PAD src0_sel:WORD_1
	v_cvt_f32_f16_e32 v242, v219
	v_cvt_f32_f16_sdwa v243, v219 dst_sel:DWORD dst_unused:UNUSED_PAD src0_sel:WORD_1
	v_pk_fma_f32 v[68:69], v[68:69], v[236:237], v[228:229]
	v_pk_fma_f32 v[70:71], v[70:71], v[238:239], v[230:231]
	v_pk_fma_f32 v[64:65], v[64:65], v[240:241], v[232:233]
	v_pk_fma_f32 v[66:67], v[66:67], v[242:243], v[234:235]
	v_cvt_pk_f16_f32 v212, v68, v69
	v_cvt_pk_f16_f32 v213, v70, v71
	v_cvt_pk_f16_f32 v214, v64, v65
	v_cvt_pk_f16_f32 v215, v66, v67
	global_store_dwordx4 v223, v[212:215], s[22:23] offset:256 sc1
	s_nop 1
	global_load_dwordx4 v[212:215], v227, s[24:25] offset:256
	global_load_dwordx4 v[216:219], v227, s[14:15] offset:256
	s_waitcnt vmcnt(21)
	v_cvt_f32_f16_e32 v228, v156
	v_cvt_f32_f16_sdwa v229, v156 dst_sel:DWORD dst_unused:UNUSED_PAD src0_sel:WORD_1
	v_cvt_f32_f16_e32 v230, v157
	v_cvt_f32_f16_sdwa v231, v157 dst_sel:DWORD dst_unused:UNUSED_PAD src0_sel:WORD_1
	v_cvt_f32_f16_e32 v232, v158
	v_cvt_f32_f16_sdwa v233, v158 dst_sel:DWORD dst_unused:UNUSED_PAD src0_sel:WORD_1
	v_cvt_f32_f16_e32 v234, v159
	v_cvt_f32_f16_sdwa v235, v159 dst_sel:DWORD dst_unused:UNUSED_PAD src0_sel:WORD_1
	v_cvt_f32_f16_e32 v236, v160
	v_cvt_f32_f16_sdwa v237, v160 dst_sel:DWORD dst_unused:UNUSED_PAD src0_sel:WORD_1
	v_cvt_f32_f16_e32 v238, v161
	v_cvt_f32_f16_sdwa v239, v161 dst_sel:DWORD dst_unused:UNUSED_PAD src0_sel:WORD_1
	v_cvt_f32_f16_e32 v240, v162
	v_cvt_f32_f16_sdwa v241, v162 dst_sel:DWORD dst_unused:UNUSED_PAD src0_sel:WORD_1
	v_cvt_f32_f16_e32 v242, v163
	v_cvt_f32_f16_sdwa v243, v163 dst_sel:DWORD dst_unused:UNUSED_PAD src0_sel:WORD_1
	v_pk_fma_f32 v[60:61], v[60:61], v[236:237], v[228:229]
	v_pk_fma_f32 v[62:63], v[62:63], v[238:239], v[230:231]
	v_pk_fma_f32 v[56:57], v[56:57], v[240:241], v[232:233]
	v_pk_fma_f32 v[58:59], v[58:59], v[242:243], v[234:235]
	v_cvt_pk_f16_f32 v156, v60, v61
	v_cvt_pk_f16_f32 v157, v62, v63
	v_cvt_pk_f16_f32 v158, v56, v57
	v_cvt_pk_f16_f32 v159, v58, v59
	global_store_dwordx4 v224, v[156:159], s[22:23] sc1
	s_nop 1
	s_waitcnt vmcnt(19)
	v_cvt_f32_f16_e32 v228, v164
	v_cvt_f32_f16_sdwa v229, v164 dst_sel:DWORD dst_unused:UNUSED_PAD src0_sel:WORD_1
	v_cvt_f32_f16_e32 v230, v165
	v_cvt_f32_f16_sdwa v231, v165 dst_sel:DWORD dst_unused:UNUSED_PAD src0_sel:WORD_1
	v_cvt_f32_f16_e32 v232, v166
	v_cvt_f32_f16_sdwa v233, v166 dst_sel:DWORD dst_unused:UNUSED_PAD src0_sel:WORD_1
	v_cvt_f32_f16_e32 v234, v167
	v_cvt_f32_f16_sdwa v235, v167 dst_sel:DWORD dst_unused:UNUSED_PAD src0_sel:WORD_1
	v_cvt_f32_f16_e32 v236, v168
	v_cvt_f32_f16_sdwa v237, v168 dst_sel:DWORD dst_unused:UNUSED_PAD src0_sel:WORD_1
	v_cvt_f32_f16_e32 v238, v169
	v_cvt_f32_f16_sdwa v239, v169 dst_sel:DWORD dst_unused:UNUSED_PAD src0_sel:WORD_1
	v_cvt_f32_f16_e32 v240, v170
	v_cvt_f32_f16_sdwa v241, v170 dst_sel:DWORD dst_unused:UNUSED_PAD src0_sel:WORD_1
	v_cvt_f32_f16_e32 v242, v171
	v_cvt_f32_f16_sdwa v243, v171 dst_sel:DWORD dst_unused:UNUSED_PAD src0_sel:WORD_1
	v_pk_fma_f32 v[52:53], v[52:53], v[236:237], v[228:229]
	v_pk_fma_f32 v[54:55], v[54:55], v[238:239], v[230:231]
	v_pk_fma_f32 v[48:49], v[48:49], v[240:241], v[232:233]
	v_pk_fma_f32 v[50:51], v[50:51], v[242:243], v[234:235]
	v_cvt_pk_f16_f32 v164, v52, v53
	v_cvt_pk_f16_f32 v165, v54, v55
	v_cvt_pk_f16_f32 v166, v48, v49
	v_cvt_pk_f16_f32 v167, v50, v51
	global_store_dwordx4 v224, v[164:167], s[22:23] offset:256 sc1
	s_nop 1
	s_waitcnt vmcnt(17)
	v_cvt_f32_f16_e32 v228, v172
	v_cvt_f32_f16_sdwa v229, v172 dst_sel:DWORD dst_unused:UNUSED_PAD src0_sel:WORD_1
	v_cvt_f32_f16_e32 v230, v173
	v_cvt_f32_f16_sdwa v231, v173 dst_sel:DWORD dst_unused:UNUSED_PAD src0_sel:WORD_1
	v_cvt_f32_f16_e32 v232, v174
	v_cvt_f32_f16_sdwa v233, v174 dst_sel:DWORD dst_unused:UNUSED_PAD src0_sel:WORD_1
	v_cvt_f32_f16_e32 v234, v175
	v_cvt_f32_f16_sdwa v235, v175 dst_sel:DWORD dst_unused:UNUSED_PAD src0_sel:WORD_1
	v_cvt_f32_f16_e32 v236, v176
	v_cvt_f32_f16_sdwa v237, v176 dst_sel:DWORD dst_unused:UNUSED_PAD src0_sel:WORD_1
	v_cvt_f32_f16_e32 v238, v177
	v_cvt_f32_f16_sdwa v239, v177 dst_sel:DWORD dst_unused:UNUSED_PAD src0_sel:WORD_1
	v_cvt_f32_f16_e32 v240, v178
	v_cvt_f32_f16_sdwa v241, v178 dst_sel:DWORD dst_unused:UNUSED_PAD src0_sel:WORD_1
	v_cvt_f32_f16_e32 v242, v179
	v_cvt_f32_f16_sdwa v243, v179 dst_sel:DWORD dst_unused:UNUSED_PAD src0_sel:WORD_1
	v_pk_fma_f32 v[44:45], v[44:45], v[236:237], v[228:229]
	v_pk_fma_f32 v[46:47], v[46:47], v[238:239], v[230:231]
	v_pk_fma_f32 v[40:41], v[40:41], v[240:241], v[232:233]
	v_pk_fma_f32 v[42:43], v[42:43], v[242:243], v[234:235]
	v_cvt_pk_f16_f32 v172, v44, v45
	v_cvt_pk_f16_f32 v173, v46, v47
	v_cvt_pk_f16_f32 v174, v40, v41
	v_cvt_pk_f16_f32 v175, v42, v43
	global_store_dwordx4 v225, v[172:175], s[22:23] sc1
	s_nop 1
	s_waitcnt vmcnt(15)
	v_cvt_f32_f16_e32 v228, v180
	v_cvt_f32_f16_sdwa v229, v180 dst_sel:DWORD dst_unused:UNUSED_PAD src0_sel:WORD_1
	v_cvt_f32_f16_e32 v230, v181
	v_cvt_f32_f16_sdwa v231, v181 dst_sel:DWORD dst_unused:UNUSED_PAD src0_sel:WORD_1
	v_cvt_f32_f16_e32 v232, v182
	v_cvt_f32_f16_sdwa v233, v182 dst_sel:DWORD dst_unused:UNUSED_PAD src0_sel:WORD_1
	v_cvt_f32_f16_e32 v234, v183
	v_cvt_f32_f16_sdwa v235, v183 dst_sel:DWORD dst_unused:UNUSED_PAD src0_sel:WORD_1
	v_cvt_f32_f16_e32 v236, v184
	v_cvt_f32_f16_sdwa v237, v184 dst_sel:DWORD dst_unused:UNUSED_PAD src0_sel:WORD_1
	v_cvt_f32_f16_e32 v238, v185
	v_cvt_f32_f16_sdwa v239, v185 dst_sel:DWORD dst_unused:UNUSED_PAD src0_sel:WORD_1
	v_cvt_f32_f16_e32 v240, v186
	v_cvt_f32_f16_sdwa v241, v186 dst_sel:DWORD dst_unused:UNUSED_PAD src0_sel:WORD_1
	v_cvt_f32_f16_e32 v242, v187
	v_cvt_f32_f16_sdwa v243, v187 dst_sel:DWORD dst_unused:UNUSED_PAD src0_sel:WORD_1
	v_pk_fma_f32 v[36:37], v[36:37], v[236:237], v[228:229]
	v_pk_fma_f32 v[38:39], v[38:39], v[238:239], v[230:231]
	v_pk_fma_f32 v[32:33], v[32:33], v[240:241], v[232:233]
	v_pk_fma_f32 v[34:35], v[34:35], v[242:243], v[234:235]
	v_cvt_pk_f16_f32 v180, v36, v37
	v_cvt_pk_f16_f32 v181, v38, v39
	v_cvt_pk_f16_f32 v182, v32, v33
	v_cvt_pk_f16_f32 v183, v34, v35
	global_store_dwordx4 v225, v[180:183], s[22:23] offset:256 sc1
	s_nop 1
	s_waitcnt vmcnt(13)
	v_cvt_f32_f16_e32 v228, v188
	v_cvt_f32_f16_sdwa v229, v188 dst_sel:DWORD dst_unused:UNUSED_PAD src0_sel:WORD_1
	v_cvt_f32_f16_e32 v230, v189
	v_cvt_f32_f16_sdwa v231, v189 dst_sel:DWORD dst_unused:UNUSED_PAD src0_sel:WORD_1
	v_cvt_f32_f16_e32 v232, v190
	v_cvt_f32_f16_sdwa v233, v190 dst_sel:DWORD dst_unused:UNUSED_PAD src0_sel:WORD_1
	v_cvt_f32_f16_e32 v234, v191
	v_cvt_f32_f16_sdwa v235, v191 dst_sel:DWORD dst_unused:UNUSED_PAD src0_sel:WORD_1
	v_cvt_f32_f16_e32 v236, v192
	v_cvt_f32_f16_sdwa v237, v192 dst_sel:DWORD dst_unused:UNUSED_PAD src0_sel:WORD_1
	v_cvt_f32_f16_e32 v238, v193
	v_cvt_f32_f16_sdwa v239, v193 dst_sel:DWORD dst_unused:UNUSED_PAD src0_sel:WORD_1
	v_cvt_f32_f16_e32 v240, v194
	v_cvt_f32_f16_sdwa v241, v194 dst_sel:DWORD dst_unused:UNUSED_PAD src0_sel:WORD_1
	v_cvt_f32_f16_e32 v242, v195
	v_cvt_f32_f16_sdwa v243, v195 dst_sel:DWORD dst_unused:UNUSED_PAD src0_sel:WORD_1
	v_pk_fma_f32 v[28:29], v[28:29], v[236:237], v[228:229]
	v_pk_fma_f32 v[30:31], v[30:31], v[238:239], v[230:231]
	v_pk_fma_f32 v[24:25], v[24:25], v[240:241], v[232:233]
	v_pk_fma_f32 v[26:27], v[26:27], v[242:243], v[234:235]
	v_cvt_pk_f16_f32 v188, v28, v29
	v_cvt_pk_f16_f32 v189, v30, v31
	v_cvt_pk_f16_f32 v190, v24, v25
	v_cvt_pk_f16_f32 v191, v26, v27
	global_store_dwordx4 v226, v[188:191], s[22:23] sc1
	s_nop 1
	s_waitcnt vmcnt(11)
	v_cvt_f32_f16_e32 v228, v196
	v_cvt_f32_f16_sdwa v229, v196 dst_sel:DWORD dst_unused:UNUSED_PAD src0_sel:WORD_1
	v_cvt_f32_f16_e32 v230, v197
	v_cvt_f32_f16_sdwa v231, v197 dst_sel:DWORD dst_unused:UNUSED_PAD src0_sel:WORD_1
	v_cvt_f32_f16_e32 v232, v198
	v_cvt_f32_f16_sdwa v233, v198 dst_sel:DWORD dst_unused:UNUSED_PAD src0_sel:WORD_1
	v_cvt_f32_f16_e32 v234, v199
	v_cvt_f32_f16_sdwa v235, v199 dst_sel:DWORD dst_unused:UNUSED_PAD src0_sel:WORD_1
	v_cvt_f32_f16_e32 v236, v200
	v_cvt_f32_f16_sdwa v237, v200 dst_sel:DWORD dst_unused:UNUSED_PAD src0_sel:WORD_1
	v_cvt_f32_f16_e32 v238, v201
	v_cvt_f32_f16_sdwa v239, v201 dst_sel:DWORD dst_unused:UNUSED_PAD src0_sel:WORD_1
	v_cvt_f32_f16_e32 v240, v202
	v_cvt_f32_f16_sdwa v241, v202 dst_sel:DWORD dst_unused:UNUSED_PAD src0_sel:WORD_1
	v_cvt_f32_f16_e32 v242, v203
	v_cvt_f32_f16_sdwa v243, v203 dst_sel:DWORD dst_unused:UNUSED_PAD src0_sel:WORD_1
	v_pk_fma_f32 v[20:21], v[20:21], v[236:237], v[228:229]
	v_pk_fma_f32 v[22:23], v[22:23], v[238:239], v[230:231]
	v_pk_fma_f32 v[16:17], v[16:17], v[240:241], v[232:233]
	v_pk_fma_f32 v[18:19], v[18:19], v[242:243], v[234:235]
	v_cvt_pk_f16_f32 v196, v20, v21
	v_cvt_pk_f16_f32 v197, v22, v23
	v_cvt_pk_f16_f32 v198, v16, v17
	v_cvt_pk_f16_f32 v199, v18, v19
	global_store_dwordx4 v226, v[196:199], s[22:23] offset:256 sc1
	s_nop 1
	s_waitcnt vmcnt(9)
	v_cvt_f32_f16_e32 v228, v204
	v_cvt_f32_f16_sdwa v229, v204 dst_sel:DWORD dst_unused:UNUSED_PAD src0_sel:WORD_1
	v_cvt_f32_f16_e32 v230, v205
	v_cvt_f32_f16_sdwa v231, v205 dst_sel:DWORD dst_unused:UNUSED_PAD src0_sel:WORD_1
	v_cvt_f32_f16_e32 v232, v206
	v_cvt_f32_f16_sdwa v233, v206 dst_sel:DWORD dst_unused:UNUSED_PAD src0_sel:WORD_1
	v_cvt_f32_f16_e32 v234, v207
	v_cvt_f32_f16_sdwa v235, v207 dst_sel:DWORD dst_unused:UNUSED_PAD src0_sel:WORD_1
	v_cvt_f32_f16_e32 v236, v208
	v_cvt_f32_f16_sdwa v237, v208 dst_sel:DWORD dst_unused:UNUSED_PAD src0_sel:WORD_1
	v_cvt_f32_f16_e32 v238, v209
	v_cvt_f32_f16_sdwa v239, v209 dst_sel:DWORD dst_unused:UNUSED_PAD src0_sel:WORD_1
	v_cvt_f32_f16_e32 v240, v210
	v_cvt_f32_f16_sdwa v241, v210 dst_sel:DWORD dst_unused:UNUSED_PAD src0_sel:WORD_1
	v_cvt_f32_f16_e32 v242, v211
	v_cvt_f32_f16_sdwa v243, v211 dst_sel:DWORD dst_unused:UNUSED_PAD src0_sel:WORD_1
	v_pk_fma_f32 v[12:13], v[12:13], v[236:237], v[228:229]
	v_pk_fma_f32 v[14:15], v[14:15], v[238:239], v[230:231]
	v_pk_fma_f32 v[8:9], v[8:9], v[240:241], v[232:233]
	v_pk_fma_f32 v[10:11], v[10:11], v[242:243], v[234:235]
	v_cvt_pk_f16_f32 v204, v12, v13
	v_cvt_pk_f16_f32 v205, v14, v15
	v_cvt_pk_f16_f32 v206, v8, v9
	v_cvt_pk_f16_f32 v207, v10, v11
	global_store_dwordx4 v227, v[204:207], s[22:23] sc1
	s_nop 1
	s_waitcnt vmcnt(7)
	v_cvt_f32_f16_e32 v228, v212
	v_cvt_f32_f16_sdwa v229, v212 dst_sel:DWORD dst_unused:UNUSED_PAD src0_sel:WORD_1
	v_cvt_f32_f16_e32 v230, v213
	v_cvt_f32_f16_sdwa v231, v213 dst_sel:DWORD dst_unused:UNUSED_PAD src0_sel:WORD_1
	v_cvt_f32_f16_e32 v232, v214
	v_cvt_f32_f16_sdwa v233, v214 dst_sel:DWORD dst_unused:UNUSED_PAD src0_sel:WORD_1
	v_cvt_f32_f16_e32 v234, v215
	v_cvt_f32_f16_sdwa v235, v215 dst_sel:DWORD dst_unused:UNUSED_PAD src0_sel:WORD_1
	v_cvt_f32_f16_e32 v236, v216
	v_cvt_f32_f16_sdwa v237, v216 dst_sel:DWORD dst_unused:UNUSED_PAD src0_sel:WORD_1
	v_cvt_f32_f16_e32 v238, v217
	v_cvt_f32_f16_sdwa v239, v217 dst_sel:DWORD dst_unused:UNUSED_PAD src0_sel:WORD_1
	v_cvt_f32_f16_e32 v240, v218
	v_cvt_f32_f16_sdwa v241, v218 dst_sel:DWORD dst_unused:UNUSED_PAD src0_sel:WORD_1
	v_cvt_f32_f16_e32 v242, v219
	v_cvt_f32_f16_sdwa v243, v219 dst_sel:DWORD dst_unused:UNUSED_PAD src0_sel:WORD_1
	v_pk_fma_f32 v[4:5], v[4:5], v[236:237], v[228:229]
	v_pk_fma_f32 v[6:7], v[6:7], v[238:239], v[230:231]
	v_pk_fma_f32 v[0:1], v[0:1], v[240:241], v[232:233]
	v_pk_fma_f32 v[2:3], v[2:3], v[242:243], v[234:235]
	v_cvt_pk_f16_f32 v212, v4, v5
	v_cvt_pk_f16_f32 v213, v6, v7
	v_cvt_pk_f16_f32 v214, v0, v1
	v_cvt_pk_f16_f32 v215, v2, v3
	global_store_dwordx4 v227, v[212:215], s[22:23] offset:256 sc1
	s_nop 1
	s_waitcnt vmcnt(0)
	s_barrier
	v_mbcnt_lo_u32_b32 v0, -1, 0
	v_mbcnt_hi_u32_b32 v0, -1, v0
	s_nop 0
	v_or_b32_e32 v0, s97, v0
	v_cmp_eq_u32_e32 vcc, 0, v0
	s_and_saveexec_b64 s[10:11], vcc
	s_cbranch_execz .LBB0_1199
	s_mov_b64 s[14:15], exec
	v_mbcnt_lo_u32_b32 v0, s14, 0
	v_mbcnt_hi_u32_b32 v0, s15, v0
	v_cmp_eq_u32_e32 vcc, 0, v0
	s_and_saveexec_b64 s[12:13], vcc
	s_cbranch_execz .LBB0_1238
	s_lshl_b32 s4, s4, 6
	s_lshl_b64 s[16:17], s[4:5], 2
	s_add_u32 s16, s56, s16
	s_addc_u32 s17, s57, s17
	s_bcnt1_i32_b64 s4, s[14:15]
	v_mov_b32_e32 v0, s4
	global_atomic_add v129, v0, s[16:17]
